# main-loop diet: all 16 LDS-DMA per iteration in SGPR-base form (2 SALU chains), B-buffer LDS reads via one invariant VGPR + offsets; no VALU left in the K-loops
# speedup vs baseline: 1.0108x; 1.0036x over previous
.LBB0_259:
	s_ashr_i32 s21, s20, 31
	s_lshl_b64 s[10:11], s[20:21], 19
	s_add_u32 s22, s46, s10
	s_addc_u32 s23, s47, s11
	s_and_b64 s[10:11], s[0:1], exec
	s_cselect_b32 s21, s23, s5
	s_cselect_b32 s26, s22, s4
	s_ashr_i32 s19, s18, 31
	s_lshl_b64 s[10:11], s[18:19], 19
	s_add_u32 s24, s72, s10
	s_addc_u32 s25, s8, s11
	s_and_b64 s[10:11], s[0:1], exec
	s_cselect_b32 s19, s25, s7
	s_cselect_b32 s27, s24, s6
	s_add_u32 s4, s4, 0x40080
	s_addc_u32 s5, s5, 0
	s_add_u32 s28, s6, 0x100
	v_mov_b32_e32 v0, 0
	s_addc_u32 s29, s7, 0
	s_mov_b32 s34, -2
	v_mov_b32_e32 v1, v0
	v_mov_b32_e32 v2, v0
	v_mov_b32_e32 v3, v0
	v_mov_b32_e32 v4, v0
	v_mov_b32_e32 v5, v0
	v_mov_b32_e32 v6, v0
	v_mov_b32_e32 v7, v0
	v_mov_b32_e32 v16, v0
	v_mov_b32_e32 v17, v0
	v_mov_b32_e32 v18, v0
	v_mov_b32_e32 v19, v0
	v_mov_b32_e32 v20, v0
	v_mov_b32_e32 v21, v0
	v_mov_b32_e32 v22, v0
	v_mov_b32_e32 v23, v0
	v_mov_b32_e32 v32, v0
	v_mov_b32_e32 v33, v0
	v_mov_b32_e32 v34, v0
	v_mov_b32_e32 v35, v0
	v_mov_b32_e32 v36, v0
	v_mov_b32_e32 v37, v0
	v_mov_b32_e32 v38, v0
	v_mov_b32_e32 v39, v0
	v_mov_b32_e32 v48, v0
	v_mov_b32_e32 v49, v0
	v_mov_b32_e32 v50, v0
	v_mov_b32_e32 v51, v0
	v_mov_b32_e32 v52, v0
	v_mov_b32_e32 v53, v0
	v_mov_b32_e32 v54, v0
	v_mov_b32_e32 v55, v0
	v_mov_b32_e32 v8, v0
	v_mov_b32_e32 v9, v0
	v_mov_b32_e32 v10, v0
	v_mov_b32_e32 v11, v0
	v_mov_b32_e32 v12, v0
	v_mov_b32_e32 v13, v0
	v_mov_b32_e32 v14, v0
	v_mov_b32_e32 v15, v0
	v_mov_b32_e32 v24, v0
	v_mov_b32_e32 v25, v0
	v_mov_b32_e32 v26, v0
	v_mov_b32_e32 v27, v0
	v_mov_b32_e32 v28, v0
	v_mov_b32_e32 v29, v0
	v_mov_b32_e32 v30, v0
	v_mov_b32_e32 v31, v0
	v_mov_b32_e32 v40, v0
	v_mov_b32_e32 v41, v0
	v_mov_b32_e32 v42, v0
	v_mov_b32_e32 v43, v0
	v_mov_b32_e32 v44, v0
	v_mov_b32_e32 v45, v0
	v_mov_b32_e32 v46, v0
	v_mov_b32_e32 v47, v0
	v_mov_b32_e32 v56, v0
	v_mov_b32_e32 v57, v0
	v_mov_b32_e32 v58, v0
	v_mov_b32_e32 v59, v0
	v_mov_b32_e32 v60, v0
	v_mov_b32_e32 v61, v0
	v_mov_b32_e32 v62, v0
	v_mov_b32_e32 v63, v0
	v_mov_b32_e32 v64, v0
	v_mov_b32_e32 v65, v0
	v_mov_b32_e32 v66, v0
	v_mov_b32_e32 v67, v0
	v_mov_b32_e32 v68, v0
	v_mov_b32_e32 v69, v0
	v_mov_b32_e32 v70, v0
	v_mov_b32_e32 v71, v0
	v_mov_b32_e32 v80, v0
	v_mov_b32_e32 v81, v0
	v_mov_b32_e32 v82, v0
	v_mov_b32_e32 v83, v0
	v_mov_b32_e32 v84, v0
	v_mov_b32_e32 v85, v0
	v_mov_b32_e32 v86, v0
	v_mov_b32_e32 v87, v0
	v_mov_b32_e32 v96, v0
	v_mov_b32_e32 v97, v0
	v_mov_b32_e32 v98, v0
	v_mov_b32_e32 v99, v0
	v_mov_b32_e32 v100, v0
	v_mov_b32_e32 v101, v0
	v_mov_b32_e32 v102, v0
	v_mov_b32_e32 v103, v0
	v_mov_b32_e32 v112, v0
	v_mov_b32_e32 v113, v0
	v_mov_b32_e32 v114, v0
	v_mov_b32_e32 v115, v0
	v_mov_b32_e32 v116, v0
	v_mov_b32_e32 v117, v0
	v_mov_b32_e32 v118, v0
	v_mov_b32_e32 v119, v0
	v_mov_b32_e32 v72, v0
	v_mov_b32_e32 v73, v0
	v_mov_b32_e32 v74, v0
	v_mov_b32_e32 v75, v0
	v_mov_b32_e32 v76, v0
	v_mov_b32_e32 v77, v0
	v_mov_b32_e32 v78, v0
	v_mov_b32_e32 v79, v0
	v_mov_b32_e32 v88, v0
	v_mov_b32_e32 v89, v0
	v_mov_b32_e32 v90, v0
	v_mov_b32_e32 v91, v0
	v_mov_b32_e32 v92, v0
	v_mov_b32_e32 v93, v0
	v_mov_b32_e32 v94, v0
	v_mov_b32_e32 v95, v0
	v_mov_b32_e32 v104, v0
	v_mov_b32_e32 v105, v0
	v_mov_b32_e32 v106, v0
	v_mov_b32_e32 v107, v0
	v_mov_b32_e32 v108, v0
	v_mov_b32_e32 v109, v0
	v_mov_b32_e32 v110, v0
	v_mov_b32_e32 v111, v0
	v_mov_b32_e32 v120, v0
	v_mov_b32_e32 v121, v0
	v_mov_b32_e32 v122, v0
	v_mov_b32_e32 v123, v0
	v_mov_b32_e32 v124, v0
	v_mov_b32_e32 v125, v0
	v_mov_b32_e32 v126, v0
	v_mov_b32_e32 v127, v0
	v_add_u32_e32 v146, 0x10000, v139
.LBB0_260:
	s_add_u32 s6, s4, 0xfffc0080
	s_addc_u32 s7, s5, -1
	s_add_i32 s35, 0, 0x10000
	s_cmp_eq_u32 s34, 12
	s_cselect_b32 s11, s21, s7
	s_cselect_b32 s10, s26, s6
	s_cselect_b32 s7, s19, s29
	s_cselect_b32 s6, s27, s28
	s_add_i32 s92, 0, 0x14000
	ds_read_b128 v[148:151], v146
	ds_read_b128 v[152:155], v146 offset:1024
	ds_read_b128 v[156:159], v146 offset:2048
	ds_read_b128 v[160:163], v146 offset:3072
	ds_read_b128 v[170:173], v146 offset:16384
	ds_read_b128 v[174:177], v146 offset:17408
	ds_read_b128 v[178:181], v146 offset:18432
	ds_read_b128 v[182:185], v146 offset:19456
	s_add_u32 s98, s6, 0x80
	s_addc_u32 s99, s7, 0
	s_add_u32 s100, s10, 0x80
	s_addc_u32 s101, s11, 0
	s_add_i32 m0, s40, 0xc000
	ds_read_b128 v[186:189], v168
	ds_read_b128 v[190:193], v168 offset:1024
	ds_read_b128 v[194:197], v168 offset:2048
	ds_read_b128 v[198:201], v168 offset:3072
	ds_read_b128 v[202:205], v168 offset:4096
	ds_read_b128 v[222:225], v168 offset:5120
	ds_read_b128 v[236:239], v168 offset:6144
	ds_read_b128 v[240:243], v168 offset:7168
	global_load_lds_dwordx4 v142, s[4:5]
	s_add_i32 m0, s40, 0xe000
	s_nop 0
	global_load_lds_dwordx4 v144, s[4:5]
	s_waitcnt vmcnt(8)
	s_waitcnt lgkmcnt(0)
	s_barrier
	s_setprio 1
	v_mfma_f32_16x16x32_bf16 v[124:127], v[148:151], v[186:189], v[124:127]
	v_mfma_f32_16x16x32_bf16 v[120:123], v[156:159], v[186:189], v[120:123]
	v_mfma_f32_16x16x32_bf16 v[108:111], v[148:151], v[194:197], v[108:111]
	v_mfma_f32_16x16x32_bf16 v[104:107], v[156:159], v[194:197], v[104:107]
	v_mfma_f32_16x16x32_bf16 v[92:95], v[148:151], v[202:205], v[92:95]
	v_mfma_f32_16x16x32_bf16 v[88:91], v[156:159], v[202:205], v[88:91]
	v_mfma_f32_16x16x32_bf16 v[76:79], v[148:151], v[236:239], v[76:79]
	v_mfma_f32_16x16x32_bf16 v[72:75], v[156:159], v[236:239], v[72:75]
	v_mfma_f32_16x16x32_bf16 v[124:127], v[152:155], v[190:193], v[124:127]
	v_mfma_f32_16x16x32_bf16 v[120:123], v[160:163], v[190:193], v[120:123]
	v_mfma_f32_16x16x32_bf16 v[108:111], v[152:155], v[198:201], v[108:111]
	v_mfma_f32_16x16x32_bf16 v[104:107], v[160:163], v[198:201], v[104:107]
	v_mfma_f32_16x16x32_bf16 v[92:95], v[152:155], v[222:225], v[92:95]
	v_mfma_f32_16x16x32_bf16 v[88:91], v[160:163], v[222:225], v[88:91]
	v_mfma_f32_16x16x32_bf16 v[76:79], v[152:155], v[240:243], v[76:79]
	v_mfma_f32_16x16x32_bf16 v[72:75], v[160:163], v[240:243], v[72:75]
	v_mfma_f32_16x16x32_bf16 v[116:119], v[170:173], v[186:189], v[116:119]
	v_mfma_f32_16x16x32_bf16 v[112:115], v[178:181], v[186:189], v[112:115]
	v_mfma_f32_16x16x32_bf16 v[100:103], v[170:173], v[194:197], v[100:103]
	v_mfma_f32_16x16x32_bf16 v[96:99], v[178:181], v[194:197], v[96:99]
	v_mfma_f32_16x16x32_bf16 v[84:87], v[170:173], v[202:205], v[84:87]
	v_mfma_f32_16x16x32_bf16 v[80:83], v[178:181], v[202:205], v[80:83]
	v_mfma_f32_16x16x32_bf16 v[68:71], v[170:173], v[236:239], v[68:71]
	v_mfma_f32_16x16x32_bf16 v[64:67], v[178:181], v[236:239], v[64:67]
	v_mfma_f32_16x16x32_bf16 v[116:119], v[174:177], v[190:193], v[116:119]
	v_mfma_f32_16x16x32_bf16 v[112:115], v[182:185], v[190:193], v[112:115]
	v_mfma_f32_16x16x32_bf16 v[100:103], v[174:177], v[198:201], v[100:103]
	v_mfma_f32_16x16x32_bf16 v[96:99], v[182:185], v[198:201], v[96:99]
	v_mfma_f32_16x16x32_bf16 v[84:87], v[174:177], v[222:225], v[84:87]
	v_mfma_f32_16x16x32_bf16 v[80:83], v[182:185], v[222:225], v[80:83]
	v_mfma_f32_16x16x32_bf16 v[68:71], v[174:177], v[240:243], v[68:71]
	v_mfma_f32_16x16x32_bf16 v[64:67], v[182:185], v[240:243], v[64:67]
	s_setprio 0
	s_barrier
	s_add_i32 s35, s35, s37
	s_mov_b32 m0, s35
	ds_read_b128 v[186:189], v168 offset:16384
	ds_read_b128 v[190:193], v168 offset:17408
	ds_read_b128 v[194:197], v168 offset:18432
	ds_read_b128 v[198:201], v168 offset:19456
	ds_read_b128 v[202:205], v168 offset:20480
	ds_read_b128 v[222:225], v168 offset:21504
	ds_read_b128 v[236:239], v168 offset:22528
	ds_read_b128 v[240:243], v168 offset:23552
	global_load_lds_dwordx4 v132, s[6:7]
	s_add_i32 m0, s35, 0x2000
	s_add_u32 vcc_lo, s6, 0x40000
	s_addc_u32 vcc_hi, s7, 0
	s_add_i32 s35, s92, s37
	global_load_lds_dwordx4 v128, s[6:7]
	s_mov_b32 m0, s35
	s_nop 0
	global_load_lds_dwordx4 v132, vcc
	s_add_i32 m0, s35, 0x2000
	s_nop 0
	global_load_lds_dwordx4 v128, vcc
	s_mov_b32 m0, s40
	s_nop 0
	global_load_lds_dwordx4 v134, s[10:11]
	s_mov_b32 m0, s41
	s_nop 0
	global_load_lds_dwordx4 v130, s[10:11]
	s_waitcnt vmcnt(8)
	s_waitcnt lgkmcnt(0)
	s_barrier
	s_setprio 1
	v_mfma_f32_16x16x32_bf16 v[60:63], v[148:151], v[186:189], v[60:63]
	v_mfma_f32_16x16x32_bf16 v[56:59], v[156:159], v[186:189], v[56:59]
	v_mfma_f32_16x16x32_bf16 v[44:47], v[148:151], v[194:197], v[44:47]
	v_mfma_f32_16x16x32_bf16 v[40:43], v[156:159], v[194:197], v[40:43]
	v_mfma_f32_16x16x32_bf16 v[28:31], v[148:151], v[202:205], v[28:31]
	v_mfma_f32_16x16x32_bf16 v[24:27], v[156:159], v[202:205], v[24:27]
	v_mfma_f32_16x16x32_bf16 v[12:15], v[148:151], v[236:239], v[12:15]
	v_mfma_f32_16x16x32_bf16 v[8:11], v[156:159], v[236:239], v[8:11]
	v_mfma_f32_16x16x32_bf16 v[60:63], v[152:155], v[190:193], v[60:63]
	v_mfma_f32_16x16x32_bf16 v[56:59], v[160:163], v[190:193], v[56:59]
	v_mfma_f32_16x16x32_bf16 v[44:47], v[152:155], v[198:201], v[44:47]
	v_mfma_f32_16x16x32_bf16 v[40:43], v[160:163], v[198:201], v[40:43]
	v_mfma_f32_16x16x32_bf16 v[28:31], v[152:155], v[222:225], v[28:31]
	v_mfma_f32_16x16x32_bf16 v[24:27], v[160:163], v[222:225], v[24:27]
	v_mfma_f32_16x16x32_bf16 v[12:15], v[152:155], v[240:243], v[12:15]
	v_mfma_f32_16x16x32_bf16 v[8:11], v[160:163], v[240:243], v[8:11]
	v_mfma_f32_16x16x32_bf16 v[52:55], v[170:173], v[186:189], v[52:55]
	v_mfma_f32_16x16x32_bf16 v[48:51], v[178:181], v[186:189], v[48:51]
	v_mfma_f32_16x16x32_bf16 v[36:39], v[170:173], v[194:197], v[36:39]
	v_mfma_f32_16x16x32_bf16 v[32:35], v[178:181], v[194:197], v[32:35]
	v_mfma_f32_16x16x32_bf16 v[20:23], v[170:173], v[202:205], v[20:23]
	v_mfma_f32_16x16x32_bf16 v[16:19], v[178:181], v[202:205], v[16:19]
	v_mfma_f32_16x16x32_bf16 v[4:7], v[170:173], v[236:239], v[4:7]
	v_mfma_f32_16x16x32_bf16 v[0:3], v[178:181], v[236:239], v[0:3]
	v_mfma_f32_16x16x32_bf16 v[52:55], v[174:177], v[190:193], v[52:55]
	v_mfma_f32_16x16x32_bf16 v[48:51], v[182:185], v[190:193], v[48:51]
	v_mfma_f32_16x16x32_bf16 v[36:39], v[174:177], v[198:201], v[36:39]
	v_mfma_f32_16x16x32_bf16 v[32:35], v[182:185], v[198:201], v[32:35]
	v_mfma_f32_16x16x32_bf16 v[20:23], v[174:177], v[222:225], v[20:23]
	v_mfma_f32_16x16x32_bf16 v[16:19], v[182:185], v[222:225], v[16:19]
	v_mfma_f32_16x16x32_bf16 v[4:7], v[174:177], v[240:243], v[4:7]
	v_mfma_f32_16x16x32_bf16 v[0:3], v[182:185], v[240:243], v[0:3]
	s_setprio 0
	s_barrier
	s_add_i32 s35, 0, 0x18000
	s_add_i32 s92, 0, 0x1c000
	ds_read_b128 v[148:151], v146 offset:32768
	ds_read_b128 v[152:155], v146 offset:33792
	ds_read_b128 v[156:159], v146 offset:34816
	ds_read_b128 v[160:163], v146 offset:35840
	ds_read_b128 v[170:173], v146 offset:49152
	ds_read_b128 v[174:177], v146 offset:50176
	ds_read_b128 v[178:181], v146 offset:51200
	ds_read_b128 v[182:185], v146 offset:52224
	s_add_u32 s10, s10, 0x40000
	s_addc_u32 s11, s11, 0
	s_mov_b32 m0, s42
	ds_read_b128 v[186:189], v168 offset:32768
	ds_read_b128 v[190:193], v168 offset:33792
	ds_read_b128 v[194:197], v168 offset:34816
	ds_read_b128 v[198:201], v168 offset:35840
	ds_read_b128 v[202:205], v168 offset:36864
	ds_read_b128 v[222:225], v168 offset:37888
	ds_read_b128 v[236:239], v168 offset:38912
	ds_read_b128 v[240:243], v168 offset:39936
	global_load_lds_dwordx4 v134, s[10:11]
	s_mov_b32 m0, s43
	s_nop 0
	global_load_lds_dwordx4 v130, s[10:11]
	s_waitcnt vmcnt(8)
	s_waitcnt lgkmcnt(0)
	s_barrier
	s_setprio 1
	v_mfma_f32_16x16x32_bf16 v[124:127], v[148:151], v[186:189], v[124:127]
	v_mfma_f32_16x16x32_bf16 v[120:123], v[156:159], v[186:189], v[120:123]
	v_mfma_f32_16x16x32_bf16 v[108:111], v[148:151], v[194:197], v[108:111]
	v_mfma_f32_16x16x32_bf16 v[104:107], v[156:159], v[194:197], v[104:107]
	v_mfma_f32_16x16x32_bf16 v[92:95], v[148:151], v[202:205], v[92:95]
	v_mfma_f32_16x16x32_bf16 v[88:91], v[156:159], v[202:205], v[88:91]
	v_mfma_f32_16x16x32_bf16 v[76:79], v[148:151], v[236:239], v[76:79]
	v_mfma_f32_16x16x32_bf16 v[72:75], v[156:159], v[236:239], v[72:75]
	v_mfma_f32_16x16x32_bf16 v[124:127], v[152:155], v[190:193], v[124:127]
	v_mfma_f32_16x16x32_bf16 v[120:123], v[160:163], v[190:193], v[120:123]
	v_mfma_f32_16x16x32_bf16 v[108:111], v[152:155], v[198:201], v[108:111]
	v_mfma_f32_16x16x32_bf16 v[104:107], v[160:163], v[198:201], v[104:107]
	v_mfma_f32_16x16x32_bf16 v[92:95], v[152:155], v[222:225], v[92:95]
	v_mfma_f32_16x16x32_bf16 v[88:91], v[160:163], v[222:225], v[88:91]
	v_mfma_f32_16x16x32_bf16 v[76:79], v[152:155], v[240:243], v[76:79]
	v_mfma_f32_16x16x32_bf16 v[72:75], v[160:163], v[240:243], v[72:75]
	v_mfma_f32_16x16x32_bf16 v[116:119], v[170:173], v[186:189], v[116:119]
	v_mfma_f32_16x16x32_bf16 v[112:115], v[178:181], v[186:189], v[112:115]
	v_mfma_f32_16x16x32_bf16 v[100:103], v[170:173], v[194:197], v[100:103]
	v_mfma_f32_16x16x32_bf16 v[96:99], v[178:181], v[194:197], v[96:99]
	v_mfma_f32_16x16x32_bf16 v[84:87], v[170:173], v[202:205], v[84:87]
	v_mfma_f32_16x16x32_bf16 v[80:83], v[178:181], v[202:205], v[80:83]
	v_mfma_f32_16x16x32_bf16 v[68:71], v[170:173], v[236:239], v[68:71]
	v_mfma_f32_16x16x32_bf16 v[64:67], v[178:181], v[236:239], v[64:67]
	v_mfma_f32_16x16x32_bf16 v[116:119], v[174:177], v[190:193], v[116:119]
	v_mfma_f32_16x16x32_bf16 v[112:115], v[182:185], v[190:193], v[112:115]
	v_mfma_f32_16x16x32_bf16 v[100:103], v[174:177], v[198:201], v[100:103]
	v_mfma_f32_16x16x32_bf16 v[96:99], v[182:185], v[198:201], v[96:99]
	v_mfma_f32_16x16x32_bf16 v[84:87], v[174:177], v[222:225], v[84:87]
	v_mfma_f32_16x16x32_bf16 v[80:83], v[182:185], v[222:225], v[80:83]
	v_mfma_f32_16x16x32_bf16 v[68:71], v[174:177], v[240:243], v[68:71]
	v_mfma_f32_16x16x32_bf16 v[64:67], v[182:185], v[240:243], v[64:67]
	s_setprio 0
	s_barrier
	s_add_i32 s10, s35, s37
	s_mov_b32 m0, s10
	ds_read_b128 v[186:189], v168 offset:49152
	ds_read_b128 v[190:193], v168 offset:50176
	ds_read_b128 v[194:197], v168 offset:51200
	ds_read_b128 v[198:201], v168 offset:52224
	ds_read_b128 v[202:205], v168 offset:53248
	ds_read_b128 v[222:225], v168 offset:54272
	ds_read_b128 v[236:239], v168 offset:55296
	ds_read_b128 v[240:243], v168 offset:56320
	global_load_lds_dwordx4 v132, s[98:99]
	s_add_i32 m0, s10, 0x2000
	s_add_u32 s6, s6, 0x40080
	s_addc_u32 s7, s7, 0
	s_add_i32 s10, s92, s37
	global_load_lds_dwordx4 v128, s[98:99]
	s_mov_b32 m0, s10
	s_nop 0
	global_load_lds_dwordx4 v132, s[6:7]
	s_add_i32 m0, s10, 0x2000
	s_nop 0
	global_load_lds_dwordx4 v128, s[6:7]
	s_mov_b32 m0, s76
	s_nop 0
	global_load_lds_dwordx4 v134, s[100:101]
	s_mov_b32 m0, s77
	s_nop 0
	global_load_lds_dwordx4 v130, s[100:101]
	s_waitcnt vmcnt(8)
	s_waitcnt lgkmcnt(0)
	s_barrier
	s_setprio 1
	v_mfma_f32_16x16x32_bf16 v[60:63], v[148:151], v[186:189], v[60:63]
	v_mfma_f32_16x16x32_bf16 v[56:59], v[156:159], v[186:189], v[56:59]
	v_mfma_f32_16x16x32_bf16 v[44:47], v[148:151], v[194:197], v[44:47]
	v_mfma_f32_16x16x32_bf16 v[40:43], v[156:159], v[194:197], v[40:43]
	v_mfma_f32_16x16x32_bf16 v[28:31], v[148:151], v[202:205], v[28:31]
	v_mfma_f32_16x16x32_bf16 v[24:27], v[156:159], v[202:205], v[24:27]
	v_mfma_f32_16x16x32_bf16 v[12:15], v[148:151], v[236:239], v[12:15]
	v_mfma_f32_16x16x32_bf16 v[8:11], v[156:159], v[236:239], v[8:11]
	v_mfma_f32_16x16x32_bf16 v[60:63], v[152:155], v[190:193], v[60:63]
	v_mfma_f32_16x16x32_bf16 v[56:59], v[160:163], v[190:193], v[56:59]
	v_mfma_f32_16x16x32_bf16 v[44:47], v[152:155], v[198:201], v[44:47]
	v_mfma_f32_16x16x32_bf16 v[40:43], v[160:163], v[198:201], v[40:43]
	v_mfma_f32_16x16x32_bf16 v[28:31], v[152:155], v[222:225], v[28:31]
	v_mfma_f32_16x16x32_bf16 v[24:27], v[160:163], v[222:225], v[24:27]
	v_mfma_f32_16x16x32_bf16 v[12:15], v[152:155], v[240:243], v[12:15]
	v_mfma_f32_16x16x32_bf16 v[8:11], v[160:163], v[240:243], v[8:11]
	v_mfma_f32_16x16x32_bf16 v[52:55], v[170:173], v[186:189], v[52:55]
	v_mfma_f32_16x16x32_bf16 v[48:51], v[178:181], v[186:189], v[48:51]
	v_mfma_f32_16x16x32_bf16 v[36:39], v[170:173], v[194:197], v[36:39]
	v_mfma_f32_16x16x32_bf16 v[32:35], v[178:181], v[194:197], v[32:35]
	v_mfma_f32_16x16x32_bf16 v[20:23], v[170:173], v[202:205], v[20:23]
	v_mfma_f32_16x16x32_bf16 v[16:19], v[178:181], v[202:205], v[16:19]
	v_mfma_f32_16x16x32_bf16 v[4:7], v[170:173], v[236:239], v[4:7]
	v_mfma_f32_16x16x32_bf16 v[0:3], v[178:181], v[236:239], v[0:3]
	v_mfma_f32_16x16x32_bf16 v[52:55], v[174:177], v[190:193], v[52:55]
	v_mfma_f32_16x16x32_bf16 v[48:51], v[182:185], v[190:193], v[48:51]
	v_mfma_f32_16x16x32_bf16 v[36:39], v[174:177], v[198:201], v[36:39]
	v_mfma_f32_16x16x32_bf16 v[32:35], v[182:185], v[198:201], v[32:35]
	v_mfma_f32_16x16x32_bf16 v[20:23], v[174:177], v[222:225], v[20:23]
	v_mfma_f32_16x16x32_bf16 v[16:19], v[182:185], v[222:225], v[16:19]
	v_mfma_f32_16x16x32_bf16 v[4:7], v[174:177], v[240:243], v[4:7]
	v_mfma_f32_16x16x32_bf16 v[0:3], v[182:185], v[240:243], v[0:3]
	s_setprio 0
	s_barrier
	s_add_i32 s34, s34, 2
	s_add_u32 s4, s4, 0x100
	s_addc_u32 s5, s5, 0
	s_add_u32 s28, s28, 0x100
	s_addc_u32 s29, s29, 0
	s_cmp_gt_u32 s34, 13
	s_cbranch_scc0 .LBB0_260
	v_and_b32_e32 v148, 15, v226
	v_bfe_u32 v149, v226, 4, 2
	v_bfe_u32 v150, v226, 6, 2
	v_lshrrev_b32_e32 v151, 8, v226
	v_lshl_add_u32 v152, v151, 6, v148
	v_lshlrev_b32_e32 v153, 2, v152
	s_lshl_b32 s4, s31, 10
	s_add_u32 s100, s96, s4
	s_addc_u32 s101, s97, 0
	global_load_dword v154, v153, s[100:101]
	global_load_dword v155, v153, s[100:101] offset:64
	global_load_dword v156, v153, s[100:101] offset:128
	global_load_dword v157, v153, s[100:101] offset:192
	global_load_dword v158, v153, s[100:101] offset:512
	global_load_dword v159, v153, s[100:101] offset:576
	global_load_dword v160, v153, s[100:101] offset:640
	global_load_dword v161, v153, s[100:101] offset:704
	s_and_b64 vcc, exec, s[16:17]
	s_cbranch_vccz .LBB0_263
	s_barrier

.LBB0_709:
	s_ashr_i32 s17, s16, 31
	s_lshl_b64 s[18:19], s[16:17], 19
	s_add_u32 s18, s86, s18
	s_addc_u32 s19, s87, s19
	s_and_b64 s[20:21], s[6:7], exec
	s_cselect_b32 s17, s19, s23
	s_cselect_b32 s70, s18, s22
	s_ashr_i32 s15, s14, 31
	s_lshl_b64 s[20:21], s[14:15], 19
	s_add_u32 s20, s28, s20
	s_addc_u32 s21, s29, s21
	s_and_b64 s[26:27], s[6:7], exec
	s_cselect_b32 s15, s21, s25
	s_cselect_b32 s80, s20, s24
	s_add_u32 s22, s22, 0x40080
	s_addc_u32 s23, s23, 0
	s_add_u32 s82, s24, 0x100
	v_mov_b32_e32 v0, 0
	s_addc_u32 s83, s25, 0
	s_mov_b32 s92, -2
	s_waitcnt lgkmcnt(0)
	v_mov_b32_e32 v1, v0
	v_mov_b32_e32 v2, v0
	v_mov_b32_e32 v3, v0
	v_mov_b32_e32 v4, v0
	v_mov_b32_e32 v5, v0
	v_mov_b32_e32 v6, v0
	v_mov_b32_e32 v7, v0
	v_mov_b32_e32 v16, v0
	v_mov_b32_e32 v17, v0
	v_mov_b32_e32 v18, v0
	v_mov_b32_e32 v19, v0
	v_mov_b32_e32 v20, v0
	v_mov_b32_e32 v21, v0
	v_mov_b32_e32 v22, v0
	v_mov_b32_e32 v23, v0
	v_mov_b32_e32 v32, v0
	v_mov_b32_e32 v33, v0
	v_mov_b32_e32 v34, v0
	v_mov_b32_e32 v35, v0
	v_mov_b32_e32 v36, v0
	v_mov_b32_e32 v37, v0
	v_mov_b32_e32 v38, v0
	v_mov_b32_e32 v39, v0
	v_mov_b32_e32 v48, v0
	v_mov_b32_e32 v49, v0
	v_mov_b32_e32 v50, v0
	v_mov_b32_e32 v51, v0
	v_mov_b32_e32 v52, v0
	v_mov_b32_e32 v53, v0
	v_mov_b32_e32 v54, v0
	v_mov_b32_e32 v55, v0
	v_mov_b32_e32 v8, v0
	v_mov_b32_e32 v9, v0
	v_mov_b32_e32 v10, v0
	v_mov_b32_e32 v11, v0
	v_mov_b32_e32 v12, v0
	v_mov_b32_e32 v13, v0
	v_mov_b32_e32 v14, v0
	v_mov_b32_e32 v15, v0
	v_mov_b32_e32 v24, v0
	v_mov_b32_e32 v25, v0
	v_mov_b32_e32 v26, v0
	v_mov_b32_e32 v27, v0
	v_mov_b32_e32 v28, v0
	v_mov_b32_e32 v29, v0
	v_mov_b32_e32 v30, v0
	v_mov_b32_e32 v31, v0
	v_mov_b32_e32 v40, v0
	v_mov_b32_e32 v41, v0
	v_mov_b32_e32 v42, v0
	v_mov_b32_e32 v43, v0
	v_mov_b32_e32 v44, v0
	v_mov_b32_e32 v45, v0
	v_mov_b32_e32 v46, v0
	v_mov_b32_e32 v47, v0
	v_mov_b32_e32 v56, v0
	v_mov_b32_e32 v57, v0
	v_mov_b32_e32 v58, v0
	v_mov_b32_e32 v59, v0
	v_mov_b32_e32 v60, v0
	v_mov_b32_e32 v61, v0
	v_mov_b32_e32 v62, v0
	v_mov_b32_e32 v63, v0
	v_mov_b32_e32 v64, v0
	v_mov_b32_e32 v65, v0
	v_mov_b32_e32 v66, v0
	v_mov_b32_e32 v67, v0
	v_mov_b32_e32 v68, v0
	v_mov_b32_e32 v69, v0
	v_mov_b32_e32 v70, v0
	v_mov_b32_e32 v71, v0
	v_mov_b32_e32 v80, v0
	v_mov_b32_e32 v81, v0
	v_mov_b32_e32 v82, v0
	v_mov_b32_e32 v83, v0
	v_mov_b32_e32 v84, v0
	v_mov_b32_e32 v85, v0
	v_mov_b32_e32 v86, v0
	v_mov_b32_e32 v87, v0
	v_mov_b32_e32 v96, v0
	v_mov_b32_e32 v97, v0
	v_mov_b32_e32 v98, v0
	v_mov_b32_e32 v99, v0
	v_mov_b32_e32 v100, v0
	v_mov_b32_e32 v101, v0
	v_mov_b32_e32 v102, v0
	v_mov_b32_e32 v103, v0
	v_mov_b32_e32 v112, v0
	v_mov_b32_e32 v113, v0
	v_mov_b32_e32 v114, v0
	v_mov_b32_e32 v115, v0
	v_mov_b32_e32 v116, v0
	v_mov_b32_e32 v117, v0
	v_mov_b32_e32 v118, v0
	v_mov_b32_e32 v119, v0
	v_mov_b32_e32 v72, v0
	v_mov_b32_e32 v73, v0
	v_mov_b32_e32 v74, v0
	v_mov_b32_e32 v75, v0
	v_mov_b32_e32 v76, v0
	v_mov_b32_e32 v77, v0
	v_mov_b32_e32 v78, v0
	v_mov_b32_e32 v79, v0
	v_mov_b32_e32 v88, v0
	v_mov_b32_e32 v89, v0
	v_mov_b32_e32 v90, v0
	v_mov_b32_e32 v91, v0
	v_mov_b32_e32 v92, v0
	v_mov_b32_e32 v93, v0
	v_mov_b32_e32 v94, v0
	v_mov_b32_e32 v95, v0
	v_mov_b32_e32 v104, v0
	v_mov_b32_e32 v105, v0
	v_mov_b32_e32 v106, v0
	v_mov_b32_e32 v107, v0
	v_mov_b32_e32 v108, v0
	v_mov_b32_e32 v109, v0
	v_mov_b32_e32 v110, v0
	v_mov_b32_e32 v111, v0
	v_mov_b32_e32 v120, v0
	v_mov_b32_e32 v121, v0
	v_mov_b32_e32 v122, v0
	v_mov_b32_e32 v123, v0
	v_mov_b32_e32 v124, v0
	v_mov_b32_e32 v125, v0
	v_mov_b32_e32 v126, v0
	v_mov_b32_e32 v127, v0
	v_add_u32_e32 v224, 0x10000, v145
.LBB0_710:
	s_add_u32 s24, s22, 0xfffc0080
	s_addc_u32 s25, s23, -1
	s_add_i32 vcc_lo, 0, 0x10000
	s_cmp_eq_u32 s92, 12
	s_cselect_b32 s27, s17, s25
	s_cselect_b32 s26, s70, s24
	s_cselect_b32 s25, s15, s83
	s_cselect_b32 s24, s80, s82
	s_add_i32 s10, 0, 0x14000
	ds_read_b128 v[138:141], v224
	ds_read_b128 v[148:151], v224 offset:1024
	ds_read_b128 v[152:155], v224 offset:2048
	ds_read_b128 v[156:159], v224 offset:3072
	ds_read_b128 v[160:163], v224 offset:16384
	ds_read_b128 v[164:167], v224 offset:17408
	ds_read_b128 v[168:171], v224 offset:18432
	ds_read_b128 v[172:175], v224 offset:19456
	s_add_u32 s98, s24, 0x80
	s_addc_u32 s99, s25, 0
	s_add_u32 s100, s26, 0x80
	s_addc_u32 s101, s27, 0
	s_add_i32 m0, s31, 0xc000
	ds_read_b128 v[176:179], v147
	ds_read_b128 v[180:183], v147 offset:1024
	ds_read_b128 v[184:187], v147 offset:2048
	ds_read_b128 v[188:191], v147 offset:3072
	ds_read_b128 v[192:195], v147 offset:4096
	ds_read_b128 v[196:199], v147 offset:5120
	ds_read_b128 v[200:203], v147 offset:6144
	ds_read_b128 v[204:207], v147 offset:7168
	global_load_lds_dwordx4 v134, s[22:23]
	s_add_i32 m0, s31, 0xe000
	s_nop 0
	global_load_lds_dwordx4 v136, s[22:23]
	s_waitcnt vmcnt(8)
	s_waitcnt lgkmcnt(0)
	s_barrier
	s_setprio 1
	v_mfma_f32_16x16x32_bf16 v[124:127], v[138:141], v[176:179], v[124:127]
	v_mfma_f32_16x16x32_bf16 v[120:123], v[152:155], v[176:179], v[120:123]
	v_mfma_f32_16x16x32_bf16 v[108:111], v[138:141], v[184:187], v[108:111]
	v_mfma_f32_16x16x32_bf16 v[104:107], v[152:155], v[184:187], v[104:107]
	v_mfma_f32_16x16x32_bf16 v[92:95], v[138:141], v[192:195], v[92:95]
	v_mfma_f32_16x16x32_bf16 v[88:91], v[152:155], v[192:195], v[88:91]
	v_mfma_f32_16x16x32_bf16 v[76:79], v[138:141], v[200:203], v[76:79]
	v_mfma_f32_16x16x32_bf16 v[72:75], v[152:155], v[200:203], v[72:75]
	v_mfma_f32_16x16x32_bf16 v[124:127], v[148:151], v[180:183], v[124:127]
	v_mfma_f32_16x16x32_bf16 v[120:123], v[156:159], v[180:183], v[120:123]
	v_mfma_f32_16x16x32_bf16 v[108:111], v[148:151], v[188:191], v[108:111]
	v_mfma_f32_16x16x32_bf16 v[104:107], v[156:159], v[188:191], v[104:107]
	v_mfma_f32_16x16x32_bf16 v[92:95], v[148:151], v[196:199], v[92:95]
	v_mfma_f32_16x16x32_bf16 v[88:91], v[156:159], v[196:199], v[88:91]
	v_mfma_f32_16x16x32_bf16 v[76:79], v[148:151], v[204:207], v[76:79]
	v_mfma_f32_16x16x32_bf16 v[72:75], v[156:159], v[204:207], v[72:75]
	v_mfma_f32_16x16x32_bf16 v[116:119], v[160:163], v[176:179], v[116:119]
	v_mfma_f32_16x16x32_bf16 v[112:115], v[168:171], v[176:179], v[112:115]
	v_mfma_f32_16x16x32_bf16 v[100:103], v[160:163], v[184:187], v[100:103]
	v_mfma_f32_16x16x32_bf16 v[96:99], v[168:171], v[184:187], v[96:99]
	v_mfma_f32_16x16x32_bf16 v[84:87], v[160:163], v[192:195], v[84:87]
	v_mfma_f32_16x16x32_bf16 v[80:83], v[168:171], v[192:195], v[80:83]
	v_mfma_f32_16x16x32_bf16 v[68:71], v[160:163], v[200:203], v[68:71]
	v_mfma_f32_16x16x32_bf16 v[64:67], v[168:171], v[200:203], v[64:67]
	v_mfma_f32_16x16x32_bf16 v[116:119], v[164:167], v[180:183], v[116:119]
	v_mfma_f32_16x16x32_bf16 v[112:115], v[172:175], v[180:183], v[112:115]
	v_mfma_f32_16x16x32_bf16 v[100:103], v[164:167], v[188:191], v[100:103]
	v_mfma_f32_16x16x32_bf16 v[96:99], v[172:175], v[188:191], v[96:99]
	v_mfma_f32_16x16x32_bf16 v[84:87], v[164:167], v[196:199], v[84:87]
	v_mfma_f32_16x16x32_bf16 v[80:83], v[172:175], v[196:199], v[80:83]
	v_mfma_f32_16x16x32_bf16 v[68:71], v[164:167], v[204:207], v[68:71]
	v_mfma_f32_16x16x32_bf16 v[64:67], v[172:175], v[204:207], v[64:67]
	s_setprio 0
	s_barrier
	s_add_i32 s11, vcc_lo, s30
	s_mov_b32 m0, s11
	ds_read_b128 v[176:179], v147 offset:16384
	ds_read_b128 v[180:183], v147 offset:17408
	ds_read_b128 v[184:187], v147 offset:18432
	ds_read_b128 v[188:191], v147 offset:19456
	ds_read_b128 v[192:195], v147 offset:20480
	ds_read_b128 v[196:199], v147 offset:21504
	ds_read_b128 v[200:203], v147 offset:22528
	ds_read_b128 v[204:207], v147 offset:23552
	global_load_lds_dwordx4 v208, s[24:25]
	s_add_i32 m0, s11, 0x2000
	s_add_u32 vcc_lo, s24, 0x40000
	s_addc_u32 vcc_hi, s25, 0
	s_add_i32 s10, s10, s30
	global_load_lds_dwordx4 v128, s[24:25]
	s_mov_b32 m0, s10
	s_nop 0
	global_load_lds_dwordx4 v208, vcc
	s_add_i32 m0, s10, 0x2000
	s_nop 0
	global_load_lds_dwordx4 v128, vcc
	s_mov_b32 m0, s31
	s_nop 0
	global_load_lds_dwordx4 v132, s[26:27]
	s_mov_b32 m0, s34
	s_nop 0
	global_load_lds_dwordx4 v130, s[26:27]
	s_waitcnt vmcnt(8)
	s_waitcnt lgkmcnt(0)
	s_barrier
	s_setprio 1
	v_mfma_f32_16x16x32_bf16 v[60:63], v[138:141], v[176:179], v[60:63]
	v_mfma_f32_16x16x32_bf16 v[56:59], v[152:155], v[176:179], v[56:59]
	v_mfma_f32_16x16x32_bf16 v[44:47], v[138:141], v[184:187], v[44:47]
	v_mfma_f32_16x16x32_bf16 v[40:43], v[152:155], v[184:187], v[40:43]
	v_mfma_f32_16x16x32_bf16 v[28:31], v[138:141], v[192:195], v[28:31]
	v_mfma_f32_16x16x32_bf16 v[24:27], v[152:155], v[192:195], v[24:27]
	v_mfma_f32_16x16x32_bf16 v[12:15], v[138:141], v[200:203], v[12:15]
	v_mfma_f32_16x16x32_bf16 v[8:11], v[152:155], v[200:203], v[8:11]
	v_mfma_f32_16x16x32_bf16 v[60:63], v[148:151], v[180:183], v[60:63]
	v_mfma_f32_16x16x32_bf16 v[56:59], v[156:159], v[180:183], v[56:59]
	v_mfma_f32_16x16x32_bf16 v[44:47], v[148:151], v[188:191], v[44:47]
	v_mfma_f32_16x16x32_bf16 v[40:43], v[156:159], v[188:191], v[40:43]
	v_mfma_f32_16x16x32_bf16 v[28:31], v[148:151], v[196:199], v[28:31]
	v_mfma_f32_16x16x32_bf16 v[24:27], v[156:159], v[196:199], v[24:27]
	v_mfma_f32_16x16x32_bf16 v[12:15], v[148:151], v[204:207], v[12:15]
	v_mfma_f32_16x16x32_bf16 v[8:11], v[156:159], v[204:207], v[8:11]
	v_mfma_f32_16x16x32_bf16 v[52:55], v[160:163], v[176:179], v[52:55]
	v_mfma_f32_16x16x32_bf16 v[48:51], v[168:171], v[176:179], v[48:51]
	v_mfma_f32_16x16x32_bf16 v[36:39], v[160:163], v[184:187], v[36:39]
	v_mfma_f32_16x16x32_bf16 v[32:35], v[168:171], v[184:187], v[32:35]
	v_mfma_f32_16x16x32_bf16 v[20:23], v[160:163], v[192:195], v[20:23]
	v_mfma_f32_16x16x32_bf16 v[16:19], v[168:171], v[192:195], v[16:19]
	v_mfma_f32_16x16x32_bf16 v[4:7], v[160:163], v[200:203], v[4:7]
	v_mfma_f32_16x16x32_bf16 v[0:3], v[168:171], v[200:203], v[0:3]
	v_mfma_f32_16x16x32_bf16 v[52:55], v[164:167], v[180:183], v[52:55]
	v_mfma_f32_16x16x32_bf16 v[48:51], v[172:175], v[180:183], v[48:51]
	v_mfma_f32_16x16x32_bf16 v[36:39], v[164:167], v[188:191], v[36:39]
	v_mfma_f32_16x16x32_bf16 v[32:35], v[172:175], v[188:191], v[32:35]
	v_mfma_f32_16x16x32_bf16 v[20:23], v[164:167], v[196:199], v[20:23]
	v_mfma_f32_16x16x32_bf16 v[16:19], v[172:175], v[196:199], v[16:19]
	v_mfma_f32_16x16x32_bf16 v[4:7], v[164:167], v[204:207], v[4:7]
	v_mfma_f32_16x16x32_bf16 v[0:3], v[172:175], v[204:207], v[0:3]
	s_setprio 0
	s_barrier
	s_add_i32 s10, 0, 0x18000
	s_add_i32 s11, 0, 0x1c000
	ds_read_b128 v[138:141], v224 offset:32768
	ds_read_b128 v[148:151], v224 offset:33792
	ds_read_b128 v[152:155], v224 offset:34816
	ds_read_b128 v[156:159], v224 offset:35840
	ds_read_b128 v[160:163], v224 offset:49152
	ds_read_b128 v[164:167], v224 offset:50176
	ds_read_b128 v[168:171], v224 offset:51200
	ds_read_b128 v[172:175], v224 offset:52224
	s_add_u32 s26, s26, 0x40000
	s_addc_u32 s27, s27, 0
	s_mov_b32 m0, s35
	ds_read_b128 v[176:179], v147 offset:32768
	ds_read_b128 v[180:183], v147 offset:33792
	ds_read_b128 v[184:187], v147 offset:34816
	ds_read_b128 v[188:191], v147 offset:35840
	ds_read_b128 v[192:195], v147 offset:36864
	ds_read_b128 v[196:199], v147 offset:37888
	ds_read_b128 v[200:203], v147 offset:38912
	ds_read_b128 v[204:207], v147 offset:39936
	global_load_lds_dwordx4 v132, s[26:27]
	s_mov_b32 m0, s36
	s_nop 0
	global_load_lds_dwordx4 v130, s[26:27]
	s_waitcnt vmcnt(8)
	s_waitcnt lgkmcnt(0)
	s_barrier
	s_setprio 1
	v_mfma_f32_16x16x32_bf16 v[124:127], v[138:141], v[176:179], v[124:127]
	v_mfma_f32_16x16x32_bf16 v[120:123], v[152:155], v[176:179], v[120:123]
	v_mfma_f32_16x16x32_bf16 v[108:111], v[138:141], v[184:187], v[108:111]
	v_mfma_f32_16x16x32_bf16 v[104:107], v[152:155], v[184:187], v[104:107]
	v_mfma_f32_16x16x32_bf16 v[92:95], v[138:141], v[192:195], v[92:95]
	v_mfma_f32_16x16x32_bf16 v[88:91], v[152:155], v[192:195], v[88:91]
	v_mfma_f32_16x16x32_bf16 v[76:79], v[138:141], v[200:203], v[76:79]
	v_mfma_f32_16x16x32_bf16 v[72:75], v[152:155], v[200:203], v[72:75]
	v_mfma_f32_16x16x32_bf16 v[124:127], v[148:151], v[180:183], v[124:127]
	v_mfma_f32_16x16x32_bf16 v[120:123], v[156:159], v[180:183], v[120:123]
	v_mfma_f32_16x16x32_bf16 v[108:111], v[148:151], v[188:191], v[108:111]
	v_mfma_f32_16x16x32_bf16 v[104:107], v[156:159], v[188:191], v[104:107]
	v_mfma_f32_16x16x32_bf16 v[92:95], v[148:151], v[196:199], v[92:95]
	v_mfma_f32_16x16x32_bf16 v[88:91], v[156:159], v[196:199], v[88:91]
	v_mfma_f32_16x16x32_bf16 v[76:79], v[148:151], v[204:207], v[76:79]
	v_mfma_f32_16x16x32_bf16 v[72:75], v[156:159], v[204:207], v[72:75]
	v_mfma_f32_16x16x32_bf16 v[116:119], v[160:163], v[176:179], v[116:119]
	v_mfma_f32_16x16x32_bf16 v[112:115], v[168:171], v[176:179], v[112:115]
	v_mfma_f32_16x16x32_bf16 v[100:103], v[160:163], v[184:187], v[100:103]
	v_mfma_f32_16x16x32_bf16 v[96:99], v[168:171], v[184:187], v[96:99]
	v_mfma_f32_16x16x32_bf16 v[84:87], v[160:163], v[192:195], v[84:87]
	v_mfma_f32_16x16x32_bf16 v[80:83], v[168:171], v[192:195], v[80:83]
	v_mfma_f32_16x16x32_bf16 v[68:71], v[160:163], v[200:203], v[68:71]
	v_mfma_f32_16x16x32_bf16 v[64:67], v[168:171], v[200:203], v[64:67]
	v_mfma_f32_16x16x32_bf16 v[116:119], v[164:167], v[180:183], v[116:119]
	v_mfma_f32_16x16x32_bf16 v[112:115], v[172:175], v[180:183], v[112:115]
	v_mfma_f32_16x16x32_bf16 v[100:103], v[164:167], v[188:191], v[100:103]
	v_mfma_f32_16x16x32_bf16 v[96:99], v[172:175], v[188:191], v[96:99]
	v_mfma_f32_16x16x32_bf16 v[84:87], v[164:167], v[196:199], v[84:87]
	v_mfma_f32_16x16x32_bf16 v[80:83], v[172:175], v[196:199], v[80:83]
	v_mfma_f32_16x16x32_bf16 v[68:71], v[164:167], v[204:207], v[68:71]
	v_mfma_f32_16x16x32_bf16 v[64:67], v[172:175], v[204:207], v[64:67]
	s_setprio 0
	s_barrier
	s_add_i32 s10, s10, s30
	s_mov_b32 m0, s10
	ds_read_b128 v[176:179], v147 offset:49152
	ds_read_b128 v[180:183], v147 offset:50176
	ds_read_b128 v[184:187], v147 offset:51200
	ds_read_b128 v[188:191], v147 offset:52224
	ds_read_b128 v[192:195], v147 offset:53248
	ds_read_b128 v[196:199], v147 offset:54272
	ds_read_b128 v[200:203], v147 offset:55296
	ds_read_b128 v[204:207], v147 offset:56320
	global_load_lds_dwordx4 v208, s[98:99]
	s_add_i32 m0, s10, 0x2000
	s_add_u32 s24, s24, 0x40080
	s_addc_u32 s25, s25, 0
	s_add_i32 s10, s11, s30
	global_load_lds_dwordx4 v128, s[98:99]
	s_mov_b32 m0, s10
	s_nop 0
	global_load_lds_dwordx4 v208, s[24:25]
	s_add_i32 m0, s10, 0x2000
	s_nop 0
	global_load_lds_dwordx4 v128, s[24:25]
	s_mov_b32 m0, s37
	s_nop 0
	global_load_lds_dwordx4 v132, s[100:101]
	s_mov_b32 m0, s40
	s_nop 0
	global_load_lds_dwordx4 v130, s[100:101]
	s_waitcnt vmcnt(8)
	s_waitcnt lgkmcnt(0)
	s_barrier
	s_setprio 1
	v_mfma_f32_16x16x32_bf16 v[60:63], v[138:141], v[176:179], v[60:63]
	v_mfma_f32_16x16x32_bf16 v[56:59], v[152:155], v[176:179], v[56:59]
	v_mfma_f32_16x16x32_bf16 v[44:47], v[138:141], v[184:187], v[44:47]
	v_mfma_f32_16x16x32_bf16 v[40:43], v[152:155], v[184:187], v[40:43]
	v_mfma_f32_16x16x32_bf16 v[28:31], v[138:141], v[192:195], v[28:31]
	v_mfma_f32_16x16x32_bf16 v[24:27], v[152:155], v[192:195], v[24:27]
	v_mfma_f32_16x16x32_bf16 v[12:15], v[138:141], v[200:203], v[12:15]
	v_mfma_f32_16x16x32_bf16 v[8:11], v[152:155], v[200:203], v[8:11]
	v_mfma_f32_16x16x32_bf16 v[60:63], v[148:151], v[180:183], v[60:63]
	v_mfma_f32_16x16x32_bf16 v[56:59], v[156:159], v[180:183], v[56:59]
	v_mfma_f32_16x16x32_bf16 v[44:47], v[148:151], v[188:191], v[44:47]
	v_mfma_f32_16x16x32_bf16 v[40:43], v[156:159], v[188:191], v[40:43]
	v_mfma_f32_16x16x32_bf16 v[28:31], v[148:151], v[196:199], v[28:31]
	v_mfma_f32_16x16x32_bf16 v[24:27], v[156:159], v[196:199], v[24:27]
	v_mfma_f32_16x16x32_bf16 v[12:15], v[148:151], v[204:207], v[12:15]
	v_mfma_f32_16x16x32_bf16 v[8:11], v[156:159], v[204:207], v[8:11]
	v_mfma_f32_16x16x32_bf16 v[52:55], v[160:163], v[176:179], v[52:55]
	v_mfma_f32_16x16x32_bf16 v[48:51], v[168:171], v[176:179], v[48:51]
	v_mfma_f32_16x16x32_bf16 v[36:39], v[160:163], v[184:187], v[36:39]
	v_mfma_f32_16x16x32_bf16 v[32:35], v[168:171], v[184:187], v[32:35]
	v_mfma_f32_16x16x32_bf16 v[20:23], v[160:163], v[192:195], v[20:23]
	v_mfma_f32_16x16x32_bf16 v[16:19], v[168:171], v[192:195], v[16:19]
	v_mfma_f32_16x16x32_bf16 v[4:7], v[160:163], v[200:203], v[4:7]
	v_mfma_f32_16x16x32_bf16 v[0:3], v[168:171], v[200:203], v[0:3]
	v_mfma_f32_16x16x32_bf16 v[52:55], v[164:167], v[180:183], v[52:55]
	v_mfma_f32_16x16x32_bf16 v[48:51], v[172:175], v[180:183], v[48:51]
	v_mfma_f32_16x16x32_bf16 v[36:39], v[164:167], v[188:191], v[36:39]
	v_mfma_f32_16x16x32_bf16 v[32:35], v[172:175], v[188:191], v[32:35]
	v_mfma_f32_16x16x32_bf16 v[20:23], v[164:167], v[196:199], v[20:23]
	v_mfma_f32_16x16x32_bf16 v[16:19], v[172:175], v[196:199], v[16:19]
	v_mfma_f32_16x16x32_bf16 v[4:7], v[164:167], v[204:207], v[4:7]
	v_mfma_f32_16x16x32_bf16 v[0:3], v[172:175], v[204:207], v[0:3]
	s_setprio 0
	s_barrier
	s_add_i32 s92, s92, 2
	s_add_u32 s22, s22, 0x100
	s_addc_u32 s23, s23, 0
	s_add_u32 s82, s82, 0x100
	s_addc_u32 s83, s83, 0
	s_cmp_gt_u32 s92, 13
	s_cbranch_scc0 .LBB0_710
	v_lshl_add_u32 v140, s43, 8, v144
	v_lshl_or_b32 v138, s42, 8, v146
	v_lshlrev_b32_e32 v139, 2, v140
	v_lshlrev_b32_e32 v140, 11, v140
	v_lshl_add_u32 v138, v138, 1, v140
	s_mov_b64 s[100:101], s[46:47]
	global_load_dwordx4 v[148:151], v138, s[100:101]
	global_load_dwordx4 v[152:155], v138, s[100:101] offset:256
	s_add_u32 s100, s100, 0x8000
	s_addc_u32 s101, s101, 0
	global_load_dwordx4 v[156:159], v138, s[100:101]
	global_load_dwordx4 v[160:163], v138, s[100:101] offset:256
	s_add_u32 s100, s100, 0x8000
	s_addc_u32 s101, s101, 0
	global_load_dwordx4 v[164:167], v138, s[100:101]
	global_load_dwordx4 v[168:171], v138, s[100:101] offset:256
	s_add_u32 s100, s100, 0x8000
	s_addc_u32 s101, s101, 0
	global_load_dwordx4 v[172:175], v138, s[100:101]
	global_load_dwordx4 v[176:179], v138, s[100:101] offset:256
	s_add_u32 s100, s100, 0x28000
	s_addc_u32 s101, s101, 0
	global_load_dwordx4 v[180:183], v138, s[100:101]
	global_load_dwordx4 v[184:187], v138, s[100:101] offset:256
	s_add_u32 s100, s100, 0x8000
	s_addc_u32 s101, s101, 0
	global_load_dwordx4 v[188:191], v138, s[100:101]
	global_load_dwordx4 v[192:195], v138, s[100:101] offset:256
	s_add_u32 s100, s100, 0x8000
	s_addc_u32 s101, s101, 0
	global_load_dwordx4 v[196:199], v138, s[100:101]
	global_load_dwordx4 v[200:203], v138, s[100:101] offset:256
	s_add_u32 s100, s100, 0x8000
	s_addc_u32 s101, s101, 0
	global_load_dwordx4 v[204:207], v138, s[100:101]
	global_load_dwordx4 v[236:239], v138, s[100:101] offset:256
	s_and_b64 vcc, exec, s[12:13]
	s_cbranch_vccz .LBB0_713
	s_barrier

.LBB0_794:
	s_ashr_i32 s15, s14, 31
	s_lshl_b64 s[16:17], s[14:15], 19
	s_add_u32 s16, s46, s16
	s_addc_u32 s17, s47, s17
	s_and_b64 s[18:19], s[4:5], exec
	s_cselect_b32 s15, s17, s21
	s_cselect_b32 s42, s16, s20
	s_ashr_i32 s13, s12, 31
	s_lshl_b64 s[18:19], s[12:13], 19
	s_add_u32 s18, s26, s18
	s_addc_u32 s19, s27, s19
	s_and_b64 s[24:25], s[4:5], exec
	s_cselect_b32 s13, s19, s23
	s_cselect_b32 s43, s18, s22
	s_add_u32 s20, s20, 0x40080
	s_addc_u32 s21, s21, 0
	s_add_u32 s70, s22, 0x100
	v_mov_b32_e32 v0, 0
	s_addc_u32 s80, s23, 0
	s_mov_b32 s82, -2
	v_mov_b32_e32 v1, v0
	v_mov_b32_e32 v2, v0
	v_mov_b32_e32 v3, v0
	v_mov_b32_e32 v4, v0
	v_mov_b32_e32 v5, v0
	v_mov_b32_e32 v6, v0
	v_mov_b32_e32 v7, v0
	v_mov_b32_e32 v16, v0
	v_mov_b32_e32 v17, v0
	v_mov_b32_e32 v18, v0
	v_mov_b32_e32 v19, v0
	v_mov_b32_e32 v20, v0
	v_mov_b32_e32 v21, v0
	v_mov_b32_e32 v22, v0
	v_mov_b32_e32 v23, v0
	v_mov_b32_e32 v32, v0
	v_mov_b32_e32 v33, v0
	v_mov_b32_e32 v34, v0
	v_mov_b32_e32 v35, v0
	v_mov_b32_e32 v36, v0
	v_mov_b32_e32 v37, v0
	v_mov_b32_e32 v38, v0
	v_mov_b32_e32 v39, v0
	v_mov_b32_e32 v48, v0
	v_mov_b32_e32 v49, v0
	v_mov_b32_e32 v50, v0
	v_mov_b32_e32 v51, v0
	v_mov_b32_e32 v52, v0
	v_mov_b32_e32 v53, v0
	v_mov_b32_e32 v54, v0
	v_mov_b32_e32 v55, v0
	v_mov_b32_e32 v8, v0
	v_mov_b32_e32 v9, v0
	v_mov_b32_e32 v10, v0
	v_mov_b32_e32 v11, v0
	v_mov_b32_e32 v12, v0
	v_mov_b32_e32 v13, v0
	v_mov_b32_e32 v14, v0
	v_mov_b32_e32 v15, v0
	v_mov_b32_e32 v24, v0
	v_mov_b32_e32 v25, v0
	v_mov_b32_e32 v26, v0
	v_mov_b32_e32 v27, v0
	v_mov_b32_e32 v28, v0
	v_mov_b32_e32 v29, v0
	v_mov_b32_e32 v30, v0
	v_mov_b32_e32 v31, v0
	v_mov_b32_e32 v40, v0
	v_mov_b32_e32 v41, v0
	v_mov_b32_e32 v42, v0
	v_mov_b32_e32 v43, v0
	v_mov_b32_e32 v44, v0
	v_mov_b32_e32 v45, v0
	v_mov_b32_e32 v46, v0
	v_mov_b32_e32 v47, v0
	v_mov_b32_e32 v56, v0
	v_mov_b32_e32 v57, v0
	v_mov_b32_e32 v58, v0
	v_mov_b32_e32 v59, v0
	v_mov_b32_e32 v60, v0
	v_mov_b32_e32 v61, v0
	v_mov_b32_e32 v62, v0
	v_mov_b32_e32 v63, v0
	v_mov_b32_e32 v64, v0
	v_mov_b32_e32 v65, v0
	v_mov_b32_e32 v66, v0
	v_mov_b32_e32 v67, v0
	v_mov_b32_e32 v68, v0
	v_mov_b32_e32 v69, v0
	v_mov_b32_e32 v70, v0
	v_mov_b32_e32 v71, v0
	v_mov_b32_e32 v80, v0
	v_mov_b32_e32 v81, v0
	v_mov_b32_e32 v82, v0
	v_mov_b32_e32 v83, v0
	v_mov_b32_e32 v84, v0
	v_mov_b32_e32 v85, v0
	v_mov_b32_e32 v86, v0
	v_mov_b32_e32 v87, v0
	v_mov_b32_e32 v96, v0
	v_mov_b32_e32 v97, v0
	v_mov_b32_e32 v98, v0
	v_mov_b32_e32 v99, v0
	v_mov_b32_e32 v100, v0
	v_mov_b32_e32 v101, v0
	v_mov_b32_e32 v102, v0
	v_mov_b32_e32 v103, v0
	v_mov_b32_e32 v112, v0
	v_mov_b32_e32 v113, v0
	v_mov_b32_e32 v114, v0
	v_mov_b32_e32 v115, v0
	v_mov_b32_e32 v116, v0
	v_mov_b32_e32 v117, v0
	v_mov_b32_e32 v118, v0
	v_mov_b32_e32 v119, v0
	v_mov_b32_e32 v72, v0
	v_mov_b32_e32 v73, v0
	v_mov_b32_e32 v74, v0
	v_mov_b32_e32 v75, v0
	v_mov_b32_e32 v76, v0
	v_mov_b32_e32 v77, v0
	v_mov_b32_e32 v78, v0
	v_mov_b32_e32 v79, v0
	v_mov_b32_e32 v88, v0
	v_mov_b32_e32 v89, v0
	v_mov_b32_e32 v90, v0
	v_mov_b32_e32 v91, v0
	v_mov_b32_e32 v92, v0
	v_mov_b32_e32 v93, v0
	v_mov_b32_e32 v94, v0
	v_mov_b32_e32 v95, v0
	v_mov_b32_e32 v104, v0
	v_mov_b32_e32 v105, v0
	v_mov_b32_e32 v106, v0
	v_mov_b32_e32 v107, v0
	v_mov_b32_e32 v108, v0
	v_mov_b32_e32 v109, v0
	v_mov_b32_e32 v110, v0
	v_mov_b32_e32 v111, v0
	v_mov_b32_e32 v120, v0
	v_mov_b32_e32 v121, v0
	v_mov_b32_e32 v122, v0
	v_mov_b32_e32 v123, v0
	v_mov_b32_e32 v124, v0
	v_mov_b32_e32 v125, v0
	v_mov_b32_e32 v126, v0
	v_mov_b32_e32 v127, v0
	v_add_u32_e32 v222, 0x10000, v141
.LBB0_795:
	s_add_u32 s10, s20, 0xfffc0080
	s_addc_u32 s11, s21, -1
	s_add_i32 s83, 0, 0x10000
	s_cmp_eq_u32 s82, 12
	s_cselect_b32 s25, s15, s11
	s_cselect_b32 s24, s42, s10
	s_cselect_b32 s23, s13, s80
	s_cselect_b32 s22, s43, s70
	s_add_i32 s10, 0, 0x14000
	ds_read_b128 v[144:147], v222
	ds_read_b128 v[148:151], v222 offset:1024
	ds_read_b128 v[152:155], v222 offset:2048
	ds_read_b128 v[156:159], v222 offset:3072
	ds_read_b128 v[160:163], v222 offset:16384
	ds_read_b128 v[164:167], v222 offset:17408
	ds_read_b128 v[168:171], v222 offset:18432
	ds_read_b128 v[172:175], v222 offset:19456
	s_add_u32 s98, s22, 0x80
	s_addc_u32 s99, s23, 0
	s_add_u32 s100, s24, 0x80
	s_addc_u32 s101, s25, 0
	s_add_i32 m0, s29, 0xc000
	ds_read_b128 v[176:179], v143
	ds_read_b128 v[180:183], v143 offset:1024
	ds_read_b128 v[184:187], v143 offset:2048
	ds_read_b128 v[188:191], v143 offset:3072
	ds_read_b128 v[192:195], v143 offset:4096
	ds_read_b128 v[196:199], v143 offset:5120
	ds_read_b128 v[200:203], v143 offset:6144
	ds_read_b128 v[204:207], v143 offset:7168
	global_load_lds_dwordx4 v134, s[20:21]
	s_add_i32 m0, s29, 0xe000
	s_nop 0
	global_load_lds_dwordx4 v136, s[20:21]
	s_waitcnt vmcnt(8)
	s_waitcnt lgkmcnt(0)
	s_barrier
	s_setprio 1
	v_mfma_f32_16x16x32_bf16 v[124:127], v[144:147], v[176:179], v[124:127]
	v_mfma_f32_16x16x32_bf16 v[120:123], v[152:155], v[176:179], v[120:123]
	v_mfma_f32_16x16x32_bf16 v[108:111], v[144:147], v[184:187], v[108:111]
	v_mfma_f32_16x16x32_bf16 v[104:107], v[152:155], v[184:187], v[104:107]
	v_mfma_f32_16x16x32_bf16 v[92:95], v[144:147], v[192:195], v[92:95]
	v_mfma_f32_16x16x32_bf16 v[88:91], v[152:155], v[192:195], v[88:91]
	v_mfma_f32_16x16x32_bf16 v[76:79], v[144:147], v[200:203], v[76:79]
	v_mfma_f32_16x16x32_bf16 v[72:75], v[152:155], v[200:203], v[72:75]
	v_mfma_f32_16x16x32_bf16 v[124:127], v[148:151], v[180:183], v[124:127]
	v_mfma_f32_16x16x32_bf16 v[120:123], v[156:159], v[180:183], v[120:123]
	v_mfma_f32_16x16x32_bf16 v[108:111], v[148:151], v[188:191], v[108:111]
	v_mfma_f32_16x16x32_bf16 v[104:107], v[156:159], v[188:191], v[104:107]
	v_mfma_f32_16x16x32_bf16 v[92:95], v[148:151], v[196:199], v[92:95]
	v_mfma_f32_16x16x32_bf16 v[88:91], v[156:159], v[196:199], v[88:91]
	v_mfma_f32_16x16x32_bf16 v[76:79], v[148:151], v[204:207], v[76:79]
	v_mfma_f32_16x16x32_bf16 v[72:75], v[156:159], v[204:207], v[72:75]
	v_mfma_f32_16x16x32_bf16 v[116:119], v[160:163], v[176:179], v[116:119]
	v_mfma_f32_16x16x32_bf16 v[112:115], v[168:171], v[176:179], v[112:115]
	v_mfma_f32_16x16x32_bf16 v[100:103], v[160:163], v[184:187], v[100:103]
	v_mfma_f32_16x16x32_bf16 v[96:99], v[168:171], v[184:187], v[96:99]
	v_mfma_f32_16x16x32_bf16 v[84:87], v[160:163], v[192:195], v[84:87]
	v_mfma_f32_16x16x32_bf16 v[80:83], v[168:171], v[192:195], v[80:83]
	v_mfma_f32_16x16x32_bf16 v[68:71], v[160:163], v[200:203], v[68:71]
	v_mfma_f32_16x16x32_bf16 v[64:67], v[168:171], v[200:203], v[64:67]
	v_mfma_f32_16x16x32_bf16 v[116:119], v[164:167], v[180:183], v[116:119]
	v_mfma_f32_16x16x32_bf16 v[112:115], v[172:175], v[180:183], v[112:115]
	v_mfma_f32_16x16x32_bf16 v[100:103], v[164:167], v[188:191], v[100:103]
	v_mfma_f32_16x16x32_bf16 v[96:99], v[172:175], v[188:191], v[96:99]
	v_mfma_f32_16x16x32_bf16 v[84:87], v[164:167], v[196:199], v[84:87]
	v_mfma_f32_16x16x32_bf16 v[80:83], v[172:175], v[196:199], v[80:83]
	v_mfma_f32_16x16x32_bf16 v[68:71], v[164:167], v[204:207], v[68:71]
	v_mfma_f32_16x16x32_bf16 v[64:67], v[172:175], v[204:207], v[64:67]
	s_setprio 0
	s_barrier
	s_add_i32 s11, s83, s28
	s_mov_b32 m0, s11
	ds_read_b128 v[176:179], v143 offset:16384
	ds_read_b128 v[180:183], v143 offset:17408
	ds_read_b128 v[184:187], v143 offset:18432
	ds_read_b128 v[188:191], v143 offset:19456
	ds_read_b128 v[192:195], v143 offset:20480
	ds_read_b128 v[196:199], v143 offset:21504
	ds_read_b128 v[200:203], v143 offset:22528
	ds_read_b128 v[204:207], v143 offset:23552
	global_load_lds_dwordx4 v208, s[22:23]
	s_add_i32 m0, s11, 0x2000
	s_add_u32 vcc_lo, s22, 0x40000
	s_addc_u32 vcc_hi, s23, 0
	s_add_i32 s10, s10, s28
	global_load_lds_dwordx4 v128, s[22:23]
	s_mov_b32 m0, s10
	s_nop 0
	global_load_lds_dwordx4 v208, vcc
	s_add_i32 m0, s10, 0x2000
	s_nop 0
	global_load_lds_dwordx4 v128, vcc
	s_mov_b32 m0, s29
	s_nop 0
	global_load_lds_dwordx4 v132, s[24:25]
	s_mov_b32 m0, s30
	s_nop 0
	global_load_lds_dwordx4 v130, s[24:25]
	s_waitcnt vmcnt(8)
	s_waitcnt lgkmcnt(0)
	s_barrier
	s_setprio 1
	v_mfma_f32_16x16x32_bf16 v[60:63], v[144:147], v[176:179], v[60:63]
	v_mfma_f32_16x16x32_bf16 v[56:59], v[152:155], v[176:179], v[56:59]
	v_mfma_f32_16x16x32_bf16 v[44:47], v[144:147], v[184:187], v[44:47]
	v_mfma_f32_16x16x32_bf16 v[40:43], v[152:155], v[184:187], v[40:43]
	v_mfma_f32_16x16x32_bf16 v[28:31], v[144:147], v[192:195], v[28:31]
	v_mfma_f32_16x16x32_bf16 v[24:27], v[152:155], v[192:195], v[24:27]
	v_mfma_f32_16x16x32_bf16 v[12:15], v[144:147], v[200:203], v[12:15]
	v_mfma_f32_16x16x32_bf16 v[8:11], v[152:155], v[200:203], v[8:11]
	v_mfma_f32_16x16x32_bf16 v[60:63], v[148:151], v[180:183], v[60:63]
	v_mfma_f32_16x16x32_bf16 v[56:59], v[156:159], v[180:183], v[56:59]
	v_mfma_f32_16x16x32_bf16 v[44:47], v[148:151], v[188:191], v[44:47]
	v_mfma_f32_16x16x32_bf16 v[40:43], v[156:159], v[188:191], v[40:43]
	v_mfma_f32_16x16x32_bf16 v[28:31], v[148:151], v[196:199], v[28:31]
	v_mfma_f32_16x16x32_bf16 v[24:27], v[156:159], v[196:199], v[24:27]
	v_mfma_f32_16x16x32_bf16 v[12:15], v[148:151], v[204:207], v[12:15]
	v_mfma_f32_16x16x32_bf16 v[8:11], v[156:159], v[204:207], v[8:11]
	v_mfma_f32_16x16x32_bf16 v[52:55], v[160:163], v[176:179], v[52:55]
	v_mfma_f32_16x16x32_bf16 v[48:51], v[168:171], v[176:179], v[48:51]
	v_mfma_f32_16x16x32_bf16 v[36:39], v[160:163], v[184:187], v[36:39]
	v_mfma_f32_16x16x32_bf16 v[32:35], v[168:171], v[184:187], v[32:35]
	v_mfma_f32_16x16x32_bf16 v[20:23], v[160:163], v[192:195], v[20:23]
	v_mfma_f32_16x16x32_bf16 v[16:19], v[168:171], v[192:195], v[16:19]
	v_mfma_f32_16x16x32_bf16 v[4:7], v[160:163], v[200:203], v[4:7]
	v_mfma_f32_16x16x32_bf16 v[0:3], v[168:171], v[200:203], v[0:3]
	v_mfma_f32_16x16x32_bf16 v[52:55], v[164:167], v[180:183], v[52:55]
	v_mfma_f32_16x16x32_bf16 v[48:51], v[172:175], v[180:183], v[48:51]
	v_mfma_f32_16x16x32_bf16 v[36:39], v[164:167], v[188:191], v[36:39]
	v_mfma_f32_16x16x32_bf16 v[32:35], v[172:175], v[188:191], v[32:35]
	v_mfma_f32_16x16x32_bf16 v[20:23], v[164:167], v[196:199], v[20:23]
	v_mfma_f32_16x16x32_bf16 v[16:19], v[172:175], v[196:199], v[16:19]
	v_mfma_f32_16x16x32_bf16 v[4:7], v[164:167], v[204:207], v[4:7]
	v_mfma_f32_16x16x32_bf16 v[0:3], v[172:175], v[204:207], v[0:3]
	s_setprio 0
	s_barrier
	s_add_i32 s10, 0, 0x18000
	s_add_i32 s11, 0, 0x1c000
	ds_read_b128 v[144:147], v222 offset:32768
	ds_read_b128 v[148:151], v222 offset:33792
	ds_read_b128 v[152:155], v222 offset:34816
	ds_read_b128 v[156:159], v222 offset:35840
	ds_read_b128 v[160:163], v222 offset:49152
	ds_read_b128 v[164:167], v222 offset:50176
	ds_read_b128 v[168:171], v222 offset:51200
	ds_read_b128 v[172:175], v222 offset:52224
	s_add_u32 s24, s24, 0x40000
	s_addc_u32 s25, s25, 0
	s_mov_b32 m0, s31
	ds_read_b128 v[176:179], v143 offset:32768
	ds_read_b128 v[180:183], v143 offset:33792
	ds_read_b128 v[184:187], v143 offset:34816
	ds_read_b128 v[188:191], v143 offset:35840
	ds_read_b128 v[192:195], v143 offset:36864
	ds_read_b128 v[196:199], v143 offset:37888
	ds_read_b128 v[200:203], v143 offset:38912
	ds_read_b128 v[204:207], v143 offset:39936
	global_load_lds_dwordx4 v132, s[24:25]
	s_mov_b32 m0, s34
	s_nop 0
	global_load_lds_dwordx4 v130, s[24:25]
	s_waitcnt vmcnt(8)
	s_waitcnt lgkmcnt(0)
	s_barrier
	s_setprio 1
	v_mfma_f32_16x16x32_bf16 v[124:127], v[144:147], v[176:179], v[124:127]
	v_mfma_f32_16x16x32_bf16 v[120:123], v[152:155], v[176:179], v[120:123]
	v_mfma_f32_16x16x32_bf16 v[108:111], v[144:147], v[184:187], v[108:111]
	v_mfma_f32_16x16x32_bf16 v[104:107], v[152:155], v[184:187], v[104:107]
	v_mfma_f32_16x16x32_bf16 v[92:95], v[144:147], v[192:195], v[92:95]
	v_mfma_f32_16x16x32_bf16 v[88:91], v[152:155], v[192:195], v[88:91]
	v_mfma_f32_16x16x32_bf16 v[76:79], v[144:147], v[200:203], v[76:79]
	v_mfma_f32_16x16x32_bf16 v[72:75], v[152:155], v[200:203], v[72:75]
	v_mfma_f32_16x16x32_bf16 v[124:127], v[148:151], v[180:183], v[124:127]
	v_mfma_f32_16x16x32_bf16 v[120:123], v[156:159], v[180:183], v[120:123]
	v_mfma_f32_16x16x32_bf16 v[108:111], v[148:151], v[188:191], v[108:111]
	v_mfma_f32_16x16x32_bf16 v[104:107], v[156:159], v[188:191], v[104:107]
	v_mfma_f32_16x16x32_bf16 v[92:95], v[148:151], v[196:199], v[92:95]
	v_mfma_f32_16x16x32_bf16 v[88:91], v[156:159], v[196:199], v[88:91]
	v_mfma_f32_16x16x32_bf16 v[76:79], v[148:151], v[204:207], v[76:79]
	v_mfma_f32_16x16x32_bf16 v[72:75], v[156:159], v[204:207], v[72:75]
	v_mfma_f32_16x16x32_bf16 v[116:119], v[160:163], v[176:179], v[116:119]
	v_mfma_f32_16x16x32_bf16 v[112:115], v[168:171], v[176:179], v[112:115]
	v_mfma_f32_16x16x32_bf16 v[100:103], v[160:163], v[184:187], v[100:103]
	v_mfma_f32_16x16x32_bf16 v[96:99], v[168:171], v[184:187], v[96:99]
	v_mfma_f32_16x16x32_bf16 v[84:87], v[160:163], v[192:195], v[84:87]
	v_mfma_f32_16x16x32_bf16 v[80:83], v[168:171], v[192:195], v[80:83]
	v_mfma_f32_16x16x32_bf16 v[68:71], v[160:163], v[200:203], v[68:71]
	v_mfma_f32_16x16x32_bf16 v[64:67], v[168:171], v[200:203], v[64:67]
	v_mfma_f32_16x16x32_bf16 v[116:119], v[164:167], v[180:183], v[116:119]
	v_mfma_f32_16x16x32_bf16 v[112:115], v[172:175], v[180:183], v[112:115]
	v_mfma_f32_16x16x32_bf16 v[100:103], v[164:167], v[188:191], v[100:103]
	v_mfma_f32_16x16x32_bf16 v[96:99], v[172:175], v[188:191], v[96:99]
	v_mfma_f32_16x16x32_bf16 v[84:87], v[164:167], v[196:199], v[84:87]
	v_mfma_f32_16x16x32_bf16 v[80:83], v[172:175], v[196:199], v[80:83]
	v_mfma_f32_16x16x32_bf16 v[68:71], v[164:167], v[204:207], v[68:71]
	v_mfma_f32_16x16x32_bf16 v[64:67], v[172:175], v[204:207], v[64:67]
	s_setprio 0
	s_barrier
	s_add_i32 s10, s10, s28
	s_mov_b32 m0, s10
	ds_read_b128 v[176:179], v143 offset:49152
	ds_read_b128 v[180:183], v143 offset:50176
	ds_read_b128 v[184:187], v143 offset:51200
	ds_read_b128 v[188:191], v143 offset:52224
	ds_read_b128 v[192:195], v143 offset:53248
	ds_read_b128 v[196:199], v143 offset:54272
	ds_read_b128 v[200:203], v143 offset:55296
	ds_read_b128 v[204:207], v143 offset:56320
	global_load_lds_dwordx4 v208, s[98:99]
	s_add_i32 m0, s10, 0x2000
	s_add_u32 s22, s22, 0x40080
	s_addc_u32 s23, s23, 0
	s_add_i32 s10, s11, s28
	global_load_lds_dwordx4 v128, s[98:99]
	s_mov_b32 m0, s10
	s_nop 0
	global_load_lds_dwordx4 v208, s[22:23]
	s_add_i32 m0, s10, 0x2000
	s_nop 0
	global_load_lds_dwordx4 v128, s[22:23]
	s_mov_b32 m0, s35
	s_nop 0
	global_load_lds_dwordx4 v132, s[100:101]
	s_mov_b32 m0, s36
	s_nop 0
	global_load_lds_dwordx4 v130, s[100:101]
	s_waitcnt vmcnt(8)
	s_waitcnt lgkmcnt(0)
	s_barrier
	s_setprio 1
	v_mfma_f32_16x16x32_bf16 v[60:63], v[144:147], v[176:179], v[60:63]
	v_mfma_f32_16x16x32_bf16 v[56:59], v[152:155], v[176:179], v[56:59]
	v_mfma_f32_16x16x32_bf16 v[44:47], v[144:147], v[184:187], v[44:47]
	v_mfma_f32_16x16x32_bf16 v[40:43], v[152:155], v[184:187], v[40:43]
	v_mfma_f32_16x16x32_bf16 v[28:31], v[144:147], v[192:195], v[28:31]
	v_mfma_f32_16x16x32_bf16 v[24:27], v[152:155], v[192:195], v[24:27]
	v_mfma_f32_16x16x32_bf16 v[12:15], v[144:147], v[200:203], v[12:15]
	v_mfma_f32_16x16x32_bf16 v[8:11], v[152:155], v[200:203], v[8:11]
	v_mfma_f32_16x16x32_bf16 v[60:63], v[148:151], v[180:183], v[60:63]
	v_mfma_f32_16x16x32_bf16 v[56:59], v[156:159], v[180:183], v[56:59]
	v_mfma_f32_16x16x32_bf16 v[44:47], v[148:151], v[188:191], v[44:47]
	v_mfma_f32_16x16x32_bf16 v[40:43], v[156:159], v[188:191], v[40:43]
	v_mfma_f32_16x16x32_bf16 v[28:31], v[148:151], v[196:199], v[28:31]
	v_mfma_f32_16x16x32_bf16 v[24:27], v[156:159], v[196:199], v[24:27]
	v_mfma_f32_16x16x32_bf16 v[12:15], v[148:151], v[204:207], v[12:15]
	v_mfma_f32_16x16x32_bf16 v[8:11], v[156:159], v[204:207], v[8:11]
	v_mfma_f32_16x16x32_bf16 v[52:55], v[160:163], v[176:179], v[52:55]
	v_mfma_f32_16x16x32_bf16 v[48:51], v[168:171], v[176:179], v[48:51]
	v_mfma_f32_16x16x32_bf16 v[36:39], v[160:163], v[184:187], v[36:39]
	v_mfma_f32_16x16x32_bf16 v[32:35], v[168:171], v[184:187], v[32:35]
	v_mfma_f32_16x16x32_bf16 v[20:23], v[160:163], v[192:195], v[20:23]
	v_mfma_f32_16x16x32_bf16 v[16:19], v[168:171], v[192:195], v[16:19]
	v_mfma_f32_16x16x32_bf16 v[4:7], v[160:163], v[200:203], v[4:7]
	v_mfma_f32_16x16x32_bf16 v[0:3], v[168:171], v[200:203], v[0:3]
	v_mfma_f32_16x16x32_bf16 v[52:55], v[164:167], v[180:183], v[52:55]
	v_mfma_f32_16x16x32_bf16 v[48:51], v[172:175], v[180:183], v[48:51]
	v_mfma_f32_16x16x32_bf16 v[36:39], v[164:167], v[188:191], v[36:39]
	v_mfma_f32_16x16x32_bf16 v[32:35], v[172:175], v[188:191], v[32:35]
	v_mfma_f32_16x16x32_bf16 v[20:23], v[164:167], v[196:199], v[20:23]
	v_mfma_f32_16x16x32_bf16 v[16:19], v[172:175], v[196:199], v[16:19]
	v_mfma_f32_16x16x32_bf16 v[4:7], v[164:167], v[204:207], v[4:7]
	v_mfma_f32_16x16x32_bf16 v[0:3], v[172:175], v[204:207], v[0:3]
	s_setprio 0
	s_barrier
	s_add_i32 s82, s82, 2
	s_add_u32 s20, s20, 0x100
	s_addc_u32 s21, s21, 0
	s_add_u32 s70, s70, 0x100
	s_addc_u32 s80, s80, 0
	s_cmp_gt_u32 s82, 13
	s_cbranch_scc0 .LBB0_795
	v_lshl_add_u32 v138, s40, 8, v140
	v_ashrrev_i32_e32 v139, 31, v138
	v_lshl_add_u64 v[146:147], v[138:139], 2, s[76:77]
	global_load_dword v160, v[146:147], off
	global_load_dword v161, v[146:147], off offset:64
	global_load_dword v162, v[146:147], off offset:128
	global_load_dword v163, v[146:147], off offset:192
	global_load_dword v164, v[146:147], off offset:512
	global_load_dword v165, v[146:147], off offset:576
	global_load_dword v166, v[146:147], off offset:640
	global_load_dword v167, v[146:147], off offset:704
	s_and_b64 vcc, exec, s[6:7]
	s_cbranch_vccz .LBB0_798
	s_barrier

.LBB0_868:
	s_ashr_i32 s19, s18, 31
	s_lshl_b64 s[20:21], s[18:19], 21
	s_add_u32 s20, s88, s20
	s_addc_u32 s21, s89, s21
	s_and_b64 s[22:23], s[6:7], exec
	s_cselect_b32 s19, s21, s25
	s_cselect_b32 s72, s20, s24
	s_ashr_i32 s17, s16, 31
	s_lshl_b64 s[22:23], s[16:17], 21
	s_add_u32 s22, s30, s22
	s_addc_u32 s23, s8, s23
	s_and_b64 s[28:29], s[6:7], exec
	s_cselect_b32 s17, s23, s27
	s_cselect_b32 s76, s22, s26
	s_add_u32 s24, s24, 0x100080
	s_addc_u32 s25, s25, 0
	s_add_u32 s77, s26, 0x100
	v_mov_b32_e32 v0, 0
	s_addc_u32 s80, s27, 0
	s_mov_b32 s82, -2
	s_waitcnt lgkmcnt(0)
	v_mov_b32_e32 v1, v0
	v_mov_b32_e32 v2, v0
	v_mov_b32_e32 v3, v0
	v_mov_b32_e32 v4, v0
	v_mov_b32_e32 v5, v0
	v_mov_b32_e32 v6, v0
	v_mov_b32_e32 v7, v0
	v_mov_b32_e32 v16, v0
	v_mov_b32_e32 v17, v0
	v_mov_b32_e32 v18, v0
	v_mov_b32_e32 v19, v0
	v_mov_b32_e32 v20, v0
	v_mov_b32_e32 v21, v0
	v_mov_b32_e32 v22, v0
	v_mov_b32_e32 v23, v0
	v_mov_b32_e32 v32, v0
	v_mov_b32_e32 v33, v0
	v_mov_b32_e32 v34, v0
	v_mov_b32_e32 v35, v0
	v_mov_b32_e32 v36, v0
	v_mov_b32_e32 v37, v0
	v_mov_b32_e32 v38, v0
	v_mov_b32_e32 v39, v0
	v_mov_b32_e32 v48, v0
	v_mov_b32_e32 v49, v0
	v_mov_b32_e32 v50, v0
	v_mov_b32_e32 v51, v0
	v_mov_b32_e32 v52, v0
	v_mov_b32_e32 v53, v0
	v_mov_b32_e32 v54, v0
	v_mov_b32_e32 v55, v0
	v_mov_b32_e32 v8, v0
	v_mov_b32_e32 v9, v0
	v_mov_b32_e32 v10, v0
	v_mov_b32_e32 v11, v0
	v_mov_b32_e32 v12, v0
	v_mov_b32_e32 v13, v0
	v_mov_b32_e32 v14, v0
	v_mov_b32_e32 v15, v0
	v_mov_b32_e32 v24, v0
	v_mov_b32_e32 v25, v0
	v_mov_b32_e32 v26, v0
	v_mov_b32_e32 v27, v0
	v_mov_b32_e32 v28, v0
	v_mov_b32_e32 v29, v0
	v_mov_b32_e32 v30, v0
	v_mov_b32_e32 v31, v0
	v_mov_b32_e32 v40, v0
	v_mov_b32_e32 v41, v0
	v_mov_b32_e32 v42, v0
	v_mov_b32_e32 v43, v0
	v_mov_b32_e32 v44, v0
	v_mov_b32_e32 v45, v0
	v_mov_b32_e32 v46, v0
	v_mov_b32_e32 v47, v0
	v_mov_b32_e32 v56, v0
	v_mov_b32_e32 v57, v0
	v_mov_b32_e32 v58, v0
	v_mov_b32_e32 v59, v0
	v_mov_b32_e32 v60, v0
	v_mov_b32_e32 v61, v0
	v_mov_b32_e32 v62, v0
	v_mov_b32_e32 v63, v0
	v_mov_b32_e32 v64, v0
	v_mov_b32_e32 v65, v0
	v_mov_b32_e32 v66, v0
	v_mov_b32_e32 v67, v0
	v_mov_b32_e32 v68, v0
	v_mov_b32_e32 v69, v0
	v_mov_b32_e32 v70, v0
	v_mov_b32_e32 v71, v0
	v_mov_b32_e32 v80, v0
	v_mov_b32_e32 v81, v0
	v_mov_b32_e32 v82, v0
	v_mov_b32_e32 v83, v0
	v_mov_b32_e32 v84, v0
	v_mov_b32_e32 v85, v0
	v_mov_b32_e32 v86, v0
	v_mov_b32_e32 v87, v0
	v_mov_b32_e32 v96, v0
	v_mov_b32_e32 v97, v0
	v_mov_b32_e32 v98, v0
	v_mov_b32_e32 v99, v0
	v_mov_b32_e32 v100, v0
	v_mov_b32_e32 v101, v0
	v_mov_b32_e32 v102, v0
	v_mov_b32_e32 v103, v0
	v_mov_b32_e32 v112, v0
	v_mov_b32_e32 v113, v0
	v_mov_b32_e32 v114, v0
	v_mov_b32_e32 v115, v0
	v_mov_b32_e32 v116, v0
	v_mov_b32_e32 v117, v0
	v_mov_b32_e32 v118, v0
	v_mov_b32_e32 v119, v0
	v_mov_b32_e32 v72, v0
	v_mov_b32_e32 v73, v0
	v_mov_b32_e32 v74, v0
	v_mov_b32_e32 v75, v0
	v_mov_b32_e32 v76, v0
	v_mov_b32_e32 v77, v0
	v_mov_b32_e32 v78, v0
	v_mov_b32_e32 v79, v0
	v_mov_b32_e32 v88, v0
	v_mov_b32_e32 v89, v0
	v_mov_b32_e32 v90, v0
	v_mov_b32_e32 v91, v0
	v_mov_b32_e32 v92, v0
	v_mov_b32_e32 v93, v0
	v_mov_b32_e32 v94, v0
	v_mov_b32_e32 v95, v0
	v_mov_b32_e32 v104, v0
	v_mov_b32_e32 v105, v0
	v_mov_b32_e32 v106, v0
	v_mov_b32_e32 v107, v0
	v_mov_b32_e32 v108, v0
	v_mov_b32_e32 v109, v0
	v_mov_b32_e32 v110, v0
	v_mov_b32_e32 v111, v0
	v_mov_b32_e32 v120, v0
	v_mov_b32_e32 v121, v0
	v_mov_b32_e32 v122, v0
	v_mov_b32_e32 v123, v0
	v_mov_b32_e32 v124, v0
	v_mov_b32_e32 v125, v0
	v_mov_b32_e32 v126, v0
	v_mov_b32_e32 v127, v0
	v_add_u32_e32 v224, 0x10000, v145
.LBB0_869:
	s_add_u32 s10, s24, 0xfff00080
	s_addc_u32 s11, s25, -1
	s_add_i32 s83, 0, 0x10000
	s_cmp_eq_u32 s82, 60
	s_cselect_b32 s29, s19, s11
	s_cselect_b32 s28, s72, s10
	s_cselect_b32 s27, s17, s80
	s_cselect_b32 s26, s76, s77
	s_add_i32 s10, 0, 0x14000
	ds_read_b128 v[138:141], v224
	ds_read_b128 v[148:151], v224 offset:1024
	ds_read_b128 v[152:155], v224 offset:2048
	ds_read_b128 v[156:159], v224 offset:3072
	ds_read_b128 v[160:163], v224 offset:16384
	ds_read_b128 v[164:167], v224 offset:17408
	ds_read_b128 v[168:171], v224 offset:18432
	ds_read_b128 v[172:175], v224 offset:19456
	s_add_u32 s98, s26, 0x80
	s_addc_u32 s99, s27, 0
	s_add_u32 s100, s28, 0x80
	s_addc_u32 s101, s29, 0
	s_add_i32 m0, s34, 0xc000
	ds_read_b128 v[176:179], v147
	ds_read_b128 v[180:183], v147 offset:1024
	ds_read_b128 v[184:187], v147 offset:2048
	ds_read_b128 v[188:191], v147 offset:3072
	ds_read_b128 v[192:195], v147 offset:4096
	ds_read_b128 v[196:199], v147 offset:5120
	ds_read_b128 v[200:203], v147 offset:6144
	ds_read_b128 v[204:207], v147 offset:7168
	global_load_lds_dwordx4 v134, s[24:25]
	s_add_i32 m0, s34, 0xe000
	s_nop 0
	global_load_lds_dwordx4 v136, s[24:25]
	s_waitcnt vmcnt(8)
	s_waitcnt lgkmcnt(0)
	s_barrier
	s_setprio 1
	v_mfma_f32_16x16x32_bf16 v[124:127], v[138:141], v[176:179], v[124:127]
	v_mfma_f32_16x16x32_bf16 v[120:123], v[152:155], v[176:179], v[120:123]
	v_mfma_f32_16x16x32_bf16 v[108:111], v[138:141], v[184:187], v[108:111]
	v_mfma_f32_16x16x32_bf16 v[104:107], v[152:155], v[184:187], v[104:107]
	v_mfma_f32_16x16x32_bf16 v[92:95], v[138:141], v[192:195], v[92:95]
	v_mfma_f32_16x16x32_bf16 v[88:91], v[152:155], v[192:195], v[88:91]
	v_mfma_f32_16x16x32_bf16 v[76:79], v[138:141], v[200:203], v[76:79]
	v_mfma_f32_16x16x32_bf16 v[72:75], v[152:155], v[200:203], v[72:75]
	v_mfma_f32_16x16x32_bf16 v[124:127], v[148:151], v[180:183], v[124:127]
	v_mfma_f32_16x16x32_bf16 v[120:123], v[156:159], v[180:183], v[120:123]
	v_mfma_f32_16x16x32_bf16 v[108:111], v[148:151], v[188:191], v[108:111]
	v_mfma_f32_16x16x32_bf16 v[104:107], v[156:159], v[188:191], v[104:107]
	v_mfma_f32_16x16x32_bf16 v[92:95], v[148:151], v[196:199], v[92:95]
	v_mfma_f32_16x16x32_bf16 v[88:91], v[156:159], v[196:199], v[88:91]
	v_mfma_f32_16x16x32_bf16 v[76:79], v[148:151], v[204:207], v[76:79]
	v_mfma_f32_16x16x32_bf16 v[72:75], v[156:159], v[204:207], v[72:75]
	v_mfma_f32_16x16x32_bf16 v[116:119], v[160:163], v[176:179], v[116:119]
	v_mfma_f32_16x16x32_bf16 v[112:115], v[168:171], v[176:179], v[112:115]
	v_mfma_f32_16x16x32_bf16 v[100:103], v[160:163], v[184:187], v[100:103]
	v_mfma_f32_16x16x32_bf16 v[96:99], v[168:171], v[184:187], v[96:99]
	v_mfma_f32_16x16x32_bf16 v[84:87], v[160:163], v[192:195], v[84:87]
	v_mfma_f32_16x16x32_bf16 v[80:83], v[168:171], v[192:195], v[80:83]
	v_mfma_f32_16x16x32_bf16 v[68:71], v[160:163], v[200:203], v[68:71]
	v_mfma_f32_16x16x32_bf16 v[64:67], v[168:171], v[200:203], v[64:67]
	v_mfma_f32_16x16x32_bf16 v[116:119], v[164:167], v[180:183], v[116:119]
	v_mfma_f32_16x16x32_bf16 v[112:115], v[172:175], v[180:183], v[112:115]
	v_mfma_f32_16x16x32_bf16 v[100:103], v[164:167], v[188:191], v[100:103]
	v_mfma_f32_16x16x32_bf16 v[96:99], v[172:175], v[188:191], v[96:99]
	v_mfma_f32_16x16x32_bf16 v[84:87], v[164:167], v[196:199], v[84:87]
	v_mfma_f32_16x16x32_bf16 v[80:83], v[172:175], v[196:199], v[80:83]
	v_mfma_f32_16x16x32_bf16 v[68:71], v[164:167], v[204:207], v[68:71]
	v_mfma_f32_16x16x32_bf16 v[64:67], v[172:175], v[204:207], v[64:67]
	s_setprio 0
	s_barrier
	s_add_i32 s11, s83, s31
	s_mov_b32 m0, s11
	ds_read_b128 v[176:179], v147 offset:16384
	ds_read_b128 v[180:183], v147 offset:17408
	ds_read_b128 v[184:187], v147 offset:18432
	ds_read_b128 v[188:191], v147 offset:19456
	ds_read_b128 v[192:195], v147 offset:20480
	ds_read_b128 v[196:199], v147 offset:21504
	ds_read_b128 v[200:203], v147 offset:22528
	ds_read_b128 v[204:207], v147 offset:23552
	global_load_lds_dwordx4 v208, s[26:27]
	s_add_i32 m0, s11, 0x2000
	s_add_u32 s96, s26, 0x100000
	s_addc_u32 s97, s27, 0
	s_add_i32 s10, s10, s31
	global_load_lds_dwordx4 v128, s[26:27]
	s_mov_b32 m0, s10
	s_nop 0
	global_load_lds_dwordx4 v208, s[96:97]
	s_add_i32 m0, s10, 0x2000
	s_nop 0
	global_load_lds_dwordx4 v128, s[96:97]
	s_mov_b32 m0, s34
	s_nop 0
	global_load_lds_dwordx4 v132, s[28:29]
	s_mov_b32 m0, s35
	s_nop 0
	global_load_lds_dwordx4 v130, s[28:29]
	s_waitcnt vmcnt(8)
	s_waitcnt lgkmcnt(0)
	s_barrier
	s_setprio 1
	v_mfma_f32_16x16x32_bf16 v[60:63], v[138:141], v[176:179], v[60:63]
	v_mfma_f32_16x16x32_bf16 v[56:59], v[152:155], v[176:179], v[56:59]
	v_mfma_f32_16x16x32_bf16 v[44:47], v[138:141], v[184:187], v[44:47]
	v_mfma_f32_16x16x32_bf16 v[40:43], v[152:155], v[184:187], v[40:43]
	v_mfma_f32_16x16x32_bf16 v[28:31], v[138:141], v[192:195], v[28:31]
	v_mfma_f32_16x16x32_bf16 v[24:27], v[152:155], v[192:195], v[24:27]
	v_mfma_f32_16x16x32_bf16 v[12:15], v[138:141], v[200:203], v[12:15]
	v_mfma_f32_16x16x32_bf16 v[8:11], v[152:155], v[200:203], v[8:11]
	v_mfma_f32_16x16x32_bf16 v[60:63], v[148:151], v[180:183], v[60:63]
	v_mfma_f32_16x16x32_bf16 v[56:59], v[156:159], v[180:183], v[56:59]
	v_mfma_f32_16x16x32_bf16 v[44:47], v[148:151], v[188:191], v[44:47]
	v_mfma_f32_16x16x32_bf16 v[40:43], v[156:159], v[188:191], v[40:43]
	v_mfma_f32_16x16x32_bf16 v[28:31], v[148:151], v[196:199], v[28:31]
	v_mfma_f32_16x16x32_bf16 v[24:27], v[156:159], v[196:199], v[24:27]
	v_mfma_f32_16x16x32_bf16 v[12:15], v[148:151], v[204:207], v[12:15]
	v_mfma_f32_16x16x32_bf16 v[8:11], v[156:159], v[204:207], v[8:11]
	v_mfma_f32_16x16x32_bf16 v[52:55], v[160:163], v[176:179], v[52:55]
	v_mfma_f32_16x16x32_bf16 v[48:51], v[168:171], v[176:179], v[48:51]
	v_mfma_f32_16x16x32_bf16 v[36:39], v[160:163], v[184:187], v[36:39]
	v_mfma_f32_16x16x32_bf16 v[32:35], v[168:171], v[184:187], v[32:35]
	v_mfma_f32_16x16x32_bf16 v[20:23], v[160:163], v[192:195], v[20:23]
	v_mfma_f32_16x16x32_bf16 v[16:19], v[168:171], v[192:195], v[16:19]
	v_mfma_f32_16x16x32_bf16 v[4:7], v[160:163], v[200:203], v[4:7]
	v_mfma_f32_16x16x32_bf16 v[0:3], v[168:171], v[200:203], v[0:3]
	v_mfma_f32_16x16x32_bf16 v[52:55], v[164:167], v[180:183], v[52:55]
	v_mfma_f32_16x16x32_bf16 v[48:51], v[172:175], v[180:183], v[48:51]
	v_mfma_f32_16x16x32_bf16 v[36:39], v[164:167], v[188:191], v[36:39]
	v_mfma_f32_16x16x32_bf16 v[32:35], v[172:175], v[188:191], v[32:35]
	v_mfma_f32_16x16x32_bf16 v[20:23], v[164:167], v[196:199], v[20:23]
	v_mfma_f32_16x16x32_bf16 v[16:19], v[172:175], v[196:199], v[16:19]
	v_mfma_f32_16x16x32_bf16 v[4:7], v[164:167], v[204:207], v[4:7]
	v_mfma_f32_16x16x32_bf16 v[0:3], v[172:175], v[204:207], v[0:3]
	s_setprio 0
	s_barrier
	s_add_i32 s10, 0, 0x18000
	s_add_i32 s11, 0, 0x1c000
	ds_read_b128 v[138:141], v224 offset:32768
	ds_read_b128 v[148:151], v224 offset:33792
	ds_read_b128 v[152:155], v224 offset:34816
	ds_read_b128 v[156:159], v224 offset:35840
	ds_read_b128 v[160:163], v224 offset:49152
	ds_read_b128 v[164:167], v224 offset:50176
	ds_read_b128 v[168:171], v224 offset:51200
	ds_read_b128 v[172:175], v224 offset:52224
	s_add_u32 s28, s28, 0x100000
	s_addc_u32 s29, s29, 0
	s_mov_b32 m0, s36
	ds_read_b128 v[176:179], v147 offset:32768
	ds_read_b128 v[180:183], v147 offset:33792
	ds_read_b128 v[184:187], v147 offset:34816
	ds_read_b128 v[188:191], v147 offset:35840
	ds_read_b128 v[192:195], v147 offset:36864
	ds_read_b128 v[196:199], v147 offset:37888
	ds_read_b128 v[200:203], v147 offset:38912
	ds_read_b128 v[204:207], v147 offset:39936
	global_load_lds_dwordx4 v132, s[28:29]
	s_mov_b32 m0, s37
	s_nop 0
	global_load_lds_dwordx4 v130, s[28:29]
	s_waitcnt vmcnt(8)
	s_waitcnt lgkmcnt(0)
	s_barrier
	s_setprio 1
	v_mfma_f32_16x16x32_bf16 v[124:127], v[138:141], v[176:179], v[124:127]
	v_mfma_f32_16x16x32_bf16 v[120:123], v[152:155], v[176:179], v[120:123]
	v_mfma_f32_16x16x32_bf16 v[108:111], v[138:141], v[184:187], v[108:111]
	v_mfma_f32_16x16x32_bf16 v[104:107], v[152:155], v[184:187], v[104:107]
	v_mfma_f32_16x16x32_bf16 v[92:95], v[138:141], v[192:195], v[92:95]
	v_mfma_f32_16x16x32_bf16 v[88:91], v[152:155], v[192:195], v[88:91]
	v_mfma_f32_16x16x32_bf16 v[76:79], v[138:141], v[200:203], v[76:79]
	v_mfma_f32_16x16x32_bf16 v[72:75], v[152:155], v[200:203], v[72:75]
	v_mfma_f32_16x16x32_bf16 v[124:127], v[148:151], v[180:183], v[124:127]
	v_mfma_f32_16x16x32_bf16 v[120:123], v[156:159], v[180:183], v[120:123]
	v_mfma_f32_16x16x32_bf16 v[108:111], v[148:151], v[188:191], v[108:111]
	v_mfma_f32_16x16x32_bf16 v[104:107], v[156:159], v[188:191], v[104:107]
	v_mfma_f32_16x16x32_bf16 v[92:95], v[148:151], v[196:199], v[92:95]
	v_mfma_f32_16x16x32_bf16 v[88:91], v[156:159], v[196:199], v[88:91]
	v_mfma_f32_16x16x32_bf16 v[76:79], v[148:151], v[204:207], v[76:79]
	v_mfma_f32_16x16x32_bf16 v[72:75], v[156:159], v[204:207], v[72:75]
	v_mfma_f32_16x16x32_bf16 v[116:119], v[160:163], v[176:179], v[116:119]
	v_mfma_f32_16x16x32_bf16 v[112:115], v[168:171], v[176:179], v[112:115]
	v_mfma_f32_16x16x32_bf16 v[100:103], v[160:163], v[184:187], v[100:103]
	v_mfma_f32_16x16x32_bf16 v[96:99], v[168:171], v[184:187], v[96:99]
	v_mfma_f32_16x16x32_bf16 v[84:87], v[160:163], v[192:195], v[84:87]
	v_mfma_f32_16x16x32_bf16 v[80:83], v[168:171], v[192:195], v[80:83]
	v_mfma_f32_16x16x32_bf16 v[68:71], v[160:163], v[200:203], v[68:71]
	v_mfma_f32_16x16x32_bf16 v[64:67], v[168:171], v[200:203], v[64:67]
	v_mfma_f32_16x16x32_bf16 v[116:119], v[164:167], v[180:183], v[116:119]
	v_mfma_f32_16x16x32_bf16 v[112:115], v[172:175], v[180:183], v[112:115]
	v_mfma_f32_16x16x32_bf16 v[100:103], v[164:167], v[188:191], v[100:103]
	v_mfma_f32_16x16x32_bf16 v[96:99], v[172:175], v[188:191], v[96:99]
	v_mfma_f32_16x16x32_bf16 v[84:87], v[164:167], v[196:199], v[84:87]
	v_mfma_f32_16x16x32_bf16 v[80:83], v[172:175], v[196:199], v[80:83]
	v_mfma_f32_16x16x32_bf16 v[68:71], v[164:167], v[204:207], v[68:71]
	v_mfma_f32_16x16x32_bf16 v[64:67], v[172:175], v[204:207], v[64:67]
	s_setprio 0
	s_barrier
	s_add_i32 s10, s10, s31
	s_mov_b32 m0, s10
	ds_read_b128 v[176:179], v147 offset:49152
	ds_read_b128 v[180:183], v147 offset:50176
	ds_read_b128 v[184:187], v147 offset:51200
	ds_read_b128 v[188:191], v147 offset:52224
	ds_read_b128 v[192:195], v147 offset:53248
	ds_read_b128 v[196:199], v147 offset:54272
	ds_read_b128 v[200:203], v147 offset:55296
	ds_read_b128 v[204:207], v147 offset:56320
	global_load_lds_dwordx4 v208, s[98:99]
	s_add_i32 m0, s10, 0x2000
	s_add_u32 s26, s26, 0x100080
	s_addc_u32 s27, s27, 0
	s_add_i32 s10, s11, s31
	global_load_lds_dwordx4 v128, s[98:99]
	s_mov_b32 m0, s10
	s_nop 0
	global_load_lds_dwordx4 v208, s[26:27]
	s_add_i32 m0, s10, 0x2000
	s_nop 0
	global_load_lds_dwordx4 v128, s[26:27]
	s_mov_b32 m0, s40
	s_nop 0
	global_load_lds_dwordx4 v132, s[100:101]
	s_mov_b32 m0, s41
	s_nop 0
	global_load_lds_dwordx4 v130, s[100:101]
	s_waitcnt vmcnt(8)
	s_waitcnt lgkmcnt(0)
	s_barrier
	s_setprio 1
	v_mfma_f32_16x16x32_bf16 v[60:63], v[138:141], v[176:179], v[60:63]
	v_mfma_f32_16x16x32_bf16 v[56:59], v[152:155], v[176:179], v[56:59]
	v_mfma_f32_16x16x32_bf16 v[44:47], v[138:141], v[184:187], v[44:47]
	v_mfma_f32_16x16x32_bf16 v[40:43], v[152:155], v[184:187], v[40:43]
	v_mfma_f32_16x16x32_bf16 v[28:31], v[138:141], v[192:195], v[28:31]
	v_mfma_f32_16x16x32_bf16 v[24:27], v[152:155], v[192:195], v[24:27]
	v_mfma_f32_16x16x32_bf16 v[12:15], v[138:141], v[200:203], v[12:15]
	v_mfma_f32_16x16x32_bf16 v[8:11], v[152:155], v[200:203], v[8:11]
	v_mfma_f32_16x16x32_bf16 v[60:63], v[148:151], v[180:183], v[60:63]
	v_mfma_f32_16x16x32_bf16 v[56:59], v[156:159], v[180:183], v[56:59]
	v_mfma_f32_16x16x32_bf16 v[44:47], v[148:151], v[188:191], v[44:47]
	v_mfma_f32_16x16x32_bf16 v[40:43], v[156:159], v[188:191], v[40:43]
	v_mfma_f32_16x16x32_bf16 v[28:31], v[148:151], v[196:199], v[28:31]
	v_mfma_f32_16x16x32_bf16 v[24:27], v[156:159], v[196:199], v[24:27]
	v_mfma_f32_16x16x32_bf16 v[12:15], v[148:151], v[204:207], v[12:15]
	v_mfma_f32_16x16x32_bf16 v[8:11], v[156:159], v[204:207], v[8:11]
	v_mfma_f32_16x16x32_bf16 v[52:55], v[160:163], v[176:179], v[52:55]
	v_mfma_f32_16x16x32_bf16 v[48:51], v[168:171], v[176:179], v[48:51]
	v_mfma_f32_16x16x32_bf16 v[36:39], v[160:163], v[184:187], v[36:39]
	v_mfma_f32_16x16x32_bf16 v[32:35], v[168:171], v[184:187], v[32:35]
	v_mfma_f32_16x16x32_bf16 v[20:23], v[160:163], v[192:195], v[20:23]
	v_mfma_f32_16x16x32_bf16 v[16:19], v[168:171], v[192:195], v[16:19]
	v_mfma_f32_16x16x32_bf16 v[4:7], v[160:163], v[200:203], v[4:7]
	v_mfma_f32_16x16x32_bf16 v[0:3], v[168:171], v[200:203], v[0:3]
	v_mfma_f32_16x16x32_bf16 v[52:55], v[164:167], v[180:183], v[52:55]
	v_mfma_f32_16x16x32_bf16 v[48:51], v[172:175], v[180:183], v[48:51]
	v_mfma_f32_16x16x32_bf16 v[36:39], v[164:167], v[188:191], v[36:39]
	v_mfma_f32_16x16x32_bf16 v[32:35], v[172:175], v[188:191], v[32:35]
	v_mfma_f32_16x16x32_bf16 v[20:23], v[164:167], v[196:199], v[20:23]
	v_mfma_f32_16x16x32_bf16 v[16:19], v[172:175], v[196:199], v[16:19]
	v_mfma_f32_16x16x32_bf16 v[4:7], v[164:167], v[204:207], v[4:7]
	v_mfma_f32_16x16x32_bf16 v[0:3], v[172:175], v[204:207], v[0:3]
	s_setprio 0
	s_barrier
	s_add_i32 s82, s82, 2
	s_add_u32 s24, s24, 0x100
	s_addc_u32 s25, s25, 0
	s_add_u32 s77, s77, 0x100
	s_addc_u32 s80, s80, 0
	s_cmp_gt_u32 s82, 61
	s_cbranch_scc0 .LBB0_869
	v_lshl_add_u32 v140, s70, 8, v144
	v_lshl_or_b32 v138, s43, 8, v146
	v_lshlrev_b32_e32 v139, 2, v140
	v_lshlrev_b32_e32 v140, 11, v140
	v_lshl_add_u32 v138, v138, 1, v140
	s_mov_b64 s[100:101], s[46:47]
	global_load_dwordx4 v[148:151], v138, s[100:101]
	global_load_dwordx4 v[152:155], v138, s[100:101] offset:256
	s_add_u32 s100, s100, 0x8000
	s_addc_u32 s101, s101, 0
	global_load_dwordx4 v[156:159], v138, s[100:101]
	global_load_dwordx4 v[160:163], v138, s[100:101] offset:256
	s_add_u32 s100, s100, 0x8000
	s_addc_u32 s101, s101, 0
	global_load_dwordx4 v[164:167], v138, s[100:101]
	global_load_dwordx4 v[168:171], v138, s[100:101] offset:256
	s_add_u32 s100, s100, 0x8000
	s_addc_u32 s101, s101, 0
	global_load_dwordx4 v[172:175], v138, s[100:101]
	global_load_dwordx4 v[176:179], v138, s[100:101] offset:256
	s_add_u32 s100, s100, 0x28000
	s_addc_u32 s101, s101, 0
	global_load_dwordx4 v[180:183], v138, s[100:101]
	global_load_dwordx4 v[184:187], v138, s[100:101] offset:256
	s_add_u32 s100, s100, 0x8000
	s_addc_u32 s101, s101, 0
	global_load_dwordx4 v[188:191], v138, s[100:101]
	global_load_dwordx4 v[192:195], v138, s[100:101] offset:256
	s_add_u32 s100, s100, 0x8000
	s_addc_u32 s101, s101, 0
	global_load_dwordx4 v[196:199], v138, s[100:101]
	global_load_dwordx4 v[200:203], v138, s[100:101] offset:256
	s_add_u32 s100, s100, 0x8000
	s_addc_u32 s101, s101, 0
	global_load_dwordx4 v[204:207], v138, s[100:101]
	global_load_dwordx4 v[236:239], v138, s[100:101] offset:256
	s_and_b64 vcc, exec, s[14:15]
	s_cbranch_vccz .LBB0_872
	s_barrier
